# GEMM K-loops: loop-carried scalar updates (k counter, slab pointers, compare) moved from behind the last barrier into the shadow of the last MFMA cluster
# baseline (speedup 1.0000x reference)
.LBB0_157:
	ds_read_b128 v[154:157], v151
	ds_read_b128 v[158:161], v151 offset:1024
	ds_read_b128 v[162:165], v151 offset:2048
	ds_read_b128 v[166:169], v151 offset:3072
	ds_read_b128 v[170:173], v152
	ds_read_b128 v[174:177], v152 offset:1024
	ds_read_b128 v[178:181], v152 offset:2048
	ds_read_b128 v[182:185], v152 offset:3072
	s_add_u32 s8, s26, 0xfffc0080
	s_addc_u32 s9, s27, -1
	s_cmp_eq_u32 s45, 12
	s_cselect_b32 s29, s13, s9
	s_cselect_b32 s28, s39, s8
	s_cselect_b32 s9, s11, s44
	s_cselect_b32 s8, s40, s41
	v_lshl_add_u64 v[144:145], s[26:27], 0, v[136:137]
	s_add_i32 m0, s16, 0xc000
	ds_read_b128 v[186:189], v153
	ds_read_b128 v[190:193], v153 offset:1024
	ds_read_b128 v[196:199], v153 offset:2048
	ds_read_b128 v[200:203], v153 offset:3072
	ds_read_b128 v[204:207], v153 offset:4096
	ds_read_b128 v[208:211], v153 offset:5120
	ds_read_b128 v[212:215], v153 offset:6144
	ds_read_b128 v[216:219], v153 offset:7168
	global_load_lds_dwordx4 v[144:145], off
	v_lshl_add_u64 v[144:145], s[26:27], 0, v[138:139]
	s_add_i32 m0, s16, 0xe000
	s_nop 0
	global_load_lds_dwordx4 v[144:145], off
	s_waitcnt vmcnt(8)
	s_waitcnt lgkmcnt(0)
	s_barrier
	s_setprio 1
	s_waitcnt lgkmcnt(0)
	v_mfma_f32_16x16x32_bf16 v[124:127], v[154:157], v[186:189], v[124:127]
	v_mfma_f32_16x16x32_bf16 v[120:123], v[162:165], v[186:189], v[120:123]
	v_mfma_f32_16x16x32_bf16 v[116:119], v[154:157], v[196:199], v[116:119]
	v_mfma_f32_16x16x32_bf16 v[108:111], v[162:165], v[196:199], v[108:111]
	v_mfma_f32_16x16x32_bf16 v[96:99], v[154:157], v[204:207], v[96:99]
	v_mfma_f32_16x16x32_bf16 v[88:91], v[162:165], v[204:207], v[88:91]
	v_mfma_f32_16x16x32_bf16 v[84:87], v[154:157], v[212:215], v[84:87]
	v_mfma_f32_16x16x32_bf16 v[76:79], v[162:165], v[212:215], v[76:79]
	v_mfma_f32_16x16x32_bf16 v[124:127], v[158:161], v[190:193], v[124:127]
	v_mfma_f32_16x16x32_bf16 v[120:123], v[166:169], v[190:193], v[120:123]
	v_mfma_f32_16x16x32_bf16 v[116:119], v[158:161], v[200:203], v[116:119]
	v_mfma_f32_16x16x32_bf16 v[108:111], v[166:169], v[200:203], v[108:111]
	v_mfma_f32_16x16x32_bf16 v[96:99], v[158:161], v[208:211], v[96:99]
	v_mfma_f32_16x16x32_bf16 v[88:91], v[166:169], v[208:211], v[88:91]
	v_mfma_f32_16x16x32_bf16 v[84:87], v[158:161], v[216:219], v[84:87]
	v_mfma_f32_16x16x32_bf16 v[76:79], v[166:169], v[216:219], v[76:79]
	s_setprio 0
	s_setprio 1
	v_mfma_f32_16x16x32_bf16 v[112:115], v[170:173], v[186:189], v[112:115]
	v_mfma_f32_16x16x32_bf16 v[104:107], v[178:181], v[186:189], v[104:107]
	v_mfma_f32_16x16x32_bf16 v[100:103], v[170:173], v[196:199], v[100:103]
	v_mfma_f32_16x16x32_bf16 v[92:95], v[178:181], v[196:199], v[92:95]
	v_mfma_f32_16x16x32_bf16 v[80:83], v[170:173], v[204:207], v[80:83]
	v_mfma_f32_16x16x32_bf16 v[72:75], v[178:181], v[204:207], v[72:75]
	v_mfma_f32_16x16x32_bf16 v[68:71], v[170:173], v[212:215], v[68:71]
	v_mfma_f32_16x16x32_bf16 v[64:67], v[178:181], v[212:215], v[64:67]
	v_mfma_f32_16x16x32_bf16 v[112:115], v[174:177], v[190:193], v[112:115]
	v_mfma_f32_16x16x32_bf16 v[104:107], v[182:185], v[190:193], v[104:107]
	v_mfma_f32_16x16x32_bf16 v[100:103], v[174:177], v[200:203], v[100:103]
	v_mfma_f32_16x16x32_bf16 v[92:95], v[182:185], v[200:203], v[92:95]
	v_mfma_f32_16x16x32_bf16 v[80:83], v[174:177], v[208:211], v[80:83]
	v_mfma_f32_16x16x32_bf16 v[72:75], v[182:185], v[208:211], v[72:75]
	v_mfma_f32_16x16x32_bf16 v[68:71], v[174:177], v[216:219], v[68:71]
	v_mfma_f32_16x16x32_bf16 v[64:67], v[182:185], v[216:219], v[64:67]
	s_setprio 0
	s_barrier
	s_add_i32 s46, s31, s3
	v_lshl_add_u64 v[144:145], s[8:9], 0, v[132:133]
	s_mov_b32 m0, s46
	ds_read_b128 v[186:189], v153 offset:16384
	ds_read_b128 v[190:193], v153 offset:17408
	ds_read_b128 v[196:199], v153 offset:18432
	ds_read_b128 v[200:203], v153 offset:19456
	ds_read_b128 v[204:207], v153 offset:20480
	ds_read_b128 v[208:211], v153 offset:21504
	ds_read_b128 v[212:215], v153 offset:22528
	ds_read_b128 v[216:219], v153 offset:23552
	global_load_lds_dwordx4 v[144:145], off
	s_add_i32 m0, s46, 0x2000
	s_add_u32 s46, s8, 0x40000
	v_lshl_add_u64 v[220:221], s[8:9], 0, v[128:129]
	s_addc_u32 s47, s9, 0
	s_add_i32 s48, s33, s3
	global_load_lds_dwordx4 v[220:221], off
	v_lshl_add_u64 v[222:223], s[46:47], 0, v[132:133]
	s_mov_b32 m0, s48
	v_lshl_add_u64 v[224:225], s[28:29], 0, v[130:131]
	global_load_lds_dwordx4 v[222:223], off
	v_lshl_add_u64 v[222:223], s[46:47], 0, v[128:129]
	s_add_i32 m0, s48, 0x2000
	s_nop 0
	global_load_lds_dwordx4 v[222:223], off
	v_lshl_add_u64 v[222:223], s[28:29], 0, v[134:135]
	s_mov_b32 m0, s16
	s_nop 0
	global_load_lds_dwordx4 v[222:223], off
	s_mov_b32 m0, s17
	s_nop 0
	global_load_lds_dwordx4 v[224:225], off
	s_waitcnt vmcnt(8)
	s_waitcnt lgkmcnt(0)
	s_barrier
	s_setprio 1
	s_waitcnt lgkmcnt(0)
	v_mfma_f32_16x16x32_bf16 v[60:63], v[154:157], v[186:189], v[60:63]
	v_mfma_f32_16x16x32_bf16 v[56:59], v[162:165], v[186:189], v[56:59]
	v_mfma_f32_16x16x32_bf16 v[52:55], v[154:157], v[196:199], v[52:55]
	v_mfma_f32_16x16x32_bf16 v[44:47], v[162:165], v[196:199], v[44:47]
	v_mfma_f32_16x16x32_bf16 v[32:35], v[154:157], v[204:207], v[32:35]
	v_mfma_f32_16x16x32_bf16 v[24:27], v[162:165], v[204:207], v[24:27]
	v_mfma_f32_16x16x32_bf16 v[20:23], v[154:157], v[212:215], v[20:23]
	v_mfma_f32_16x16x32_bf16 v[12:15], v[162:165], v[212:215], v[12:15]
	v_mfma_f32_16x16x32_bf16 v[60:63], v[158:161], v[190:193], v[60:63]
	v_mfma_f32_16x16x32_bf16 v[56:59], v[166:169], v[190:193], v[56:59]
	v_mfma_f32_16x16x32_bf16 v[52:55], v[158:161], v[200:203], v[52:55]
	v_mfma_f32_16x16x32_bf16 v[44:47], v[166:169], v[200:203], v[44:47]
	v_mfma_f32_16x16x32_bf16 v[32:35], v[158:161], v[208:211], v[32:35]
	v_mfma_f32_16x16x32_bf16 v[24:27], v[166:169], v[208:211], v[24:27]
	v_mfma_f32_16x16x32_bf16 v[20:23], v[158:161], v[216:219], v[20:23]
	v_mfma_f32_16x16x32_bf16 v[12:15], v[166:169], v[216:219], v[12:15]
	s_setprio 0
	s_setprio 1
	v_mfma_f32_16x16x32_bf16 v[48:51], v[170:173], v[186:189], v[48:51]
	v_mfma_f32_16x16x32_bf16 v[40:43], v[178:181], v[186:189], v[40:43]
	v_mfma_f32_16x16x32_bf16 v[36:39], v[170:173], v[196:199], v[36:39]
	v_mfma_f32_16x16x32_bf16 v[28:31], v[178:181], v[196:199], v[28:31]
	v_mfma_f32_16x16x32_bf16 v[16:19], v[170:173], v[204:207], v[16:19]
	v_mfma_f32_16x16x32_bf16 v[8:11], v[178:181], v[204:207], v[8:11]
	v_mfma_f32_16x16x32_bf16 v[4:7], v[170:173], v[212:215], v[4:7]
	v_mfma_f32_16x16x32_bf16 v[0:3], v[178:181], v[212:215], v[0:3]
	v_mfma_f32_16x16x32_bf16 v[48:51], v[174:177], v[190:193], v[48:51]
	v_mfma_f32_16x16x32_bf16 v[40:43], v[182:185], v[190:193], v[40:43]
	v_mfma_f32_16x16x32_bf16 v[36:39], v[174:177], v[200:203], v[36:39]
	v_mfma_f32_16x16x32_bf16 v[28:31], v[182:185], v[200:203], v[28:31]
	v_mfma_f32_16x16x32_bf16 v[16:19], v[174:177], v[208:211], v[16:19]
	v_mfma_f32_16x16x32_bf16 v[8:11], v[182:185], v[208:211], v[8:11]
	v_mfma_f32_16x16x32_bf16 v[4:7], v[174:177], v[216:219], v[4:7]
	v_mfma_f32_16x16x32_bf16 v[0:3], v[182:185], v[216:219], v[0:3]
	s_setprio 0
	s_barrier
	s_add_i32 s46, 0, 0x18000
	s_add_i32 s47, 0, 0x1c000
	v_add_u32_e32 v166, s46, v148
	v_add_u32_e32 v182, s47, v148
	ds_read_b128 v[154:157], v166
	ds_read_b128 v[158:161], v166 offset:1024
	ds_read_b128 v[162:165], v166 offset:2048
	ds_read_b128 v[166:169], v166 offset:3072
	ds_read_b128 v[170:173], v182
	ds_read_b128 v[174:177], v182 offset:1024
	ds_read_b128 v[178:181], v182 offset:2048
	ds_read_b128 v[182:185], v182 offset:3072
	s_add_u32 s28, s28, 0x40000
	s_addc_u32 s29, s29, 0
	s_mov_b32 m0, s18
	v_lshl_add_u64 v[226:227], s[28:29], 0, v[134:135]
	ds_read_b128 v[186:189], v153 offset:32768
	ds_read_b128 v[190:193], v153 offset:33792
	ds_read_b128 v[196:199], v153 offset:34816
	ds_read_b128 v[200:203], v153 offset:35840
	ds_read_b128 v[204:207], v153 offset:36864
	ds_read_b128 v[208:211], v153 offset:37888
	ds_read_b128 v[212:215], v153 offset:38912
	ds_read_b128 v[216:219], v153 offset:39936
	global_load_lds_dwordx4 v[226:227], off
	v_lshl_add_u64 v[226:227], s[28:29], 0, v[130:131]
	s_mov_b32 m0, s19
	s_nop 0
	global_load_lds_dwordx4 v[226:227], off
	s_waitcnt vmcnt(8)
	s_waitcnt lgkmcnt(0)
	s_barrier
	s_setprio 1
	s_waitcnt lgkmcnt(0)
	v_mfma_f32_16x16x32_bf16 v[124:127], v[154:157], v[186:189], v[124:127]
	v_mfma_f32_16x16x32_bf16 v[120:123], v[162:165], v[186:189], v[120:123]
	v_mfma_f32_16x16x32_bf16 v[116:119], v[154:157], v[196:199], v[116:119]
	v_mfma_f32_16x16x32_bf16 v[108:111], v[162:165], v[196:199], v[108:111]
	v_mfma_f32_16x16x32_bf16 v[96:99], v[154:157], v[204:207], v[96:99]
	v_mfma_f32_16x16x32_bf16 v[88:91], v[162:165], v[204:207], v[88:91]
	v_mfma_f32_16x16x32_bf16 v[84:87], v[154:157], v[212:215], v[84:87]
	v_mfma_f32_16x16x32_bf16 v[76:79], v[162:165], v[212:215], v[76:79]
	v_mfma_f32_16x16x32_bf16 v[124:127], v[158:161], v[190:193], v[124:127]
	v_mfma_f32_16x16x32_bf16 v[120:123], v[166:169], v[190:193], v[120:123]
	v_mfma_f32_16x16x32_bf16 v[116:119], v[158:161], v[200:203], v[116:119]
	v_mfma_f32_16x16x32_bf16 v[108:111], v[166:169], v[200:203], v[108:111]
	v_mfma_f32_16x16x32_bf16 v[96:99], v[158:161], v[208:211], v[96:99]
	v_mfma_f32_16x16x32_bf16 v[88:91], v[166:169], v[208:211], v[88:91]
	v_mfma_f32_16x16x32_bf16 v[84:87], v[158:161], v[216:219], v[84:87]
	v_mfma_f32_16x16x32_bf16 v[76:79], v[166:169], v[216:219], v[76:79]
	s_setprio 0
	s_setprio 1
	v_mfma_f32_16x16x32_bf16 v[112:115], v[170:173], v[186:189], v[112:115]
	v_mfma_f32_16x16x32_bf16 v[104:107], v[178:181], v[186:189], v[104:107]
	v_mfma_f32_16x16x32_bf16 v[100:103], v[170:173], v[196:199], v[100:103]
	v_mfma_f32_16x16x32_bf16 v[92:95], v[178:181], v[196:199], v[92:95]
	v_mfma_f32_16x16x32_bf16 v[80:83], v[170:173], v[204:207], v[80:83]
	v_mfma_f32_16x16x32_bf16 v[72:75], v[178:181], v[204:207], v[72:75]
	v_mfma_f32_16x16x32_bf16 v[68:71], v[170:173], v[212:215], v[68:71]
	v_mfma_f32_16x16x32_bf16 v[64:67], v[178:181], v[212:215], v[64:67]
	v_mfma_f32_16x16x32_bf16 v[112:115], v[174:177], v[190:193], v[112:115]
	v_mfma_f32_16x16x32_bf16 v[104:107], v[182:185], v[190:193], v[104:107]
	v_mfma_f32_16x16x32_bf16 v[100:103], v[174:177], v[200:203], v[100:103]
	v_mfma_f32_16x16x32_bf16 v[92:95], v[182:185], v[200:203], v[92:95]
	v_mfma_f32_16x16x32_bf16 v[80:83], v[174:177], v[208:211], v[80:83]
	v_mfma_f32_16x16x32_bf16 v[72:75], v[182:185], v[208:211], v[72:75]
	v_mfma_f32_16x16x32_bf16 v[68:71], v[174:177], v[216:219], v[68:71]
	v_mfma_f32_16x16x32_bf16 v[64:67], v[182:185], v[216:219], v[64:67]
	s_setprio 0
	s_barrier
	s_add_i32 s28, s46, s3
	v_lshl_add_u64 v[144:145], v[144:145], 0, s[4:5]
	s_mov_b32 m0, s28
	ds_read_b128 v[186:189], v153 offset:49152
	ds_read_b128 v[190:193], v153 offset:50176
	ds_read_b128 v[196:199], v153 offset:51200
	ds_read_b128 v[200:203], v153 offset:52224
	ds_read_b128 v[204:207], v153 offset:53248
	ds_read_b128 v[208:211], v153 offset:54272
	ds_read_b128 v[212:215], v153 offset:55296
	ds_read_b128 v[216:219], v153 offset:56320
	global_load_lds_dwordx4 v[144:145], off
	s_add_i32 m0, s28, 0x2000
	s_add_u32 s8, s8, 0x40080
	v_lshl_add_u64 v[144:145], v[220:221], 0, s[4:5]
	s_addc_u32 s9, s9, 0
	s_add_i32 s28, s47, s3
	global_load_lds_dwordx4 v[144:145], off
	v_lshl_add_u64 v[144:145], s[8:9], 0, v[132:133]
	s_mov_b32 m0, s28
	s_nop 0
	global_load_lds_dwordx4 v[144:145], off
	v_lshl_add_u64 v[144:145], s[8:9], 0, v[128:129]
	s_add_i32 m0, s28, 0x2000
	s_nop 0
	global_load_lds_dwordx4 v[144:145], off
	v_lshl_add_u64 v[144:145], v[222:223], 0, s[4:5]
	s_mov_b32 m0, s25
	s_nop 0
	global_load_lds_dwordx4 v[144:145], off
	v_lshl_add_u64 v[144:145], v[224:225], 0, s[4:5]
	s_mov_b32 m0, s30
	s_nop 0
	global_load_lds_dwordx4 v[144:145], off
	s_waitcnt vmcnt(8)
	s_waitcnt lgkmcnt(0)
	s_barrier
	s_setprio 1
	s_waitcnt lgkmcnt(0)
	v_mfma_f32_16x16x32_bf16 v[60:63], v[154:157], v[186:189], v[60:63]
	s_add_i32 s45, s45, 2
	v_mfma_f32_16x16x32_bf16 v[56:59], v[162:165], v[186:189], v[56:59]
	s_add_u32 s26, s26, 0x100
	v_mfma_f32_16x16x32_bf16 v[52:55], v[154:157], v[196:199], v[52:55]
	s_addc_u32 s27, s27, 0
	v_mfma_f32_16x16x32_bf16 v[44:47], v[162:165], v[196:199], v[44:47]
	s_add_u32 s41, s41, 0x100
	v_mfma_f32_16x16x32_bf16 v[32:35], v[154:157], v[204:207], v[32:35]
	s_addc_u32 s44, s44, 0
	v_mfma_f32_16x16x32_bf16 v[24:27], v[162:165], v[204:207], v[24:27]
	s_cmp_gt_u32 s45, 13
	v_mfma_f32_16x16x32_bf16 v[20:23], v[154:157], v[212:215], v[20:23]
	v_mfma_f32_16x16x32_bf16 v[12:15], v[162:165], v[212:215], v[12:15]
	v_mfma_f32_16x16x32_bf16 v[60:63], v[158:161], v[190:193], v[60:63]
	v_mfma_f32_16x16x32_bf16 v[56:59], v[166:169], v[190:193], v[56:59]
	v_mfma_f32_16x16x32_bf16 v[52:55], v[158:161], v[200:203], v[52:55]
	v_mfma_f32_16x16x32_bf16 v[44:47], v[166:169], v[200:203], v[44:47]
	v_mfma_f32_16x16x32_bf16 v[32:35], v[158:161], v[208:211], v[32:35]
	v_mfma_f32_16x16x32_bf16 v[24:27], v[166:169], v[208:211], v[24:27]
	v_mfma_f32_16x16x32_bf16 v[20:23], v[158:161], v[216:219], v[20:23]
	v_mfma_f32_16x16x32_bf16 v[12:15], v[166:169], v[216:219], v[12:15]
	s_setprio 0
	s_setprio 1
	v_mfma_f32_16x16x32_bf16 v[48:51], v[170:173], v[186:189], v[48:51]
	v_mfma_f32_16x16x32_bf16 v[40:43], v[178:181], v[186:189], v[40:43]
	v_mfma_f32_16x16x32_bf16 v[36:39], v[170:173], v[196:199], v[36:39]
	v_mfma_f32_16x16x32_bf16 v[28:31], v[178:181], v[196:199], v[28:31]
	v_mfma_f32_16x16x32_bf16 v[16:19], v[170:173], v[204:207], v[16:19]
	v_mfma_f32_16x16x32_bf16 v[8:11], v[178:181], v[204:207], v[8:11]
	v_mfma_f32_16x16x32_bf16 v[4:7], v[170:173], v[212:215], v[4:7]
	v_mfma_f32_16x16x32_bf16 v[0:3], v[178:181], v[212:215], v[0:3]
	v_mfma_f32_16x16x32_bf16 v[48:51], v[174:177], v[190:193], v[48:51]
	v_mfma_f32_16x16x32_bf16 v[40:43], v[182:185], v[190:193], v[40:43]
	v_mfma_f32_16x16x32_bf16 v[36:39], v[174:177], v[200:203], v[36:39]
	v_mfma_f32_16x16x32_bf16 v[28:31], v[182:185], v[200:203], v[28:31]
	v_mfma_f32_16x16x32_bf16 v[16:19], v[174:177], v[208:211], v[16:19]
	v_mfma_f32_16x16x32_bf16 v[8:11], v[182:185], v[208:211], v[8:11]
	v_mfma_f32_16x16x32_bf16 v[4:7], v[174:177], v[216:219], v[4:7]
	v_mfma_f32_16x16x32_bf16 v[0:3], v[182:185], v[216:219], v[0:3]
	s_setprio 0
	s_barrier
	s_cbranch_scc0 .LBB0_157
	s_and_b64 vcc, exec, s[6:7]
	s_cbranch_vccz .LBB0_160
	s_barrier

.LBB0_666:
	ds_read_b128 v[144:147], v153
	ds_read_b128 v[162:165], v153 offset:1024
	ds_read_b128 v[166:169], v153 offset:2048
	ds_read_b128 v[170:173], v153 offset:3072
	ds_read_b128 v[174:177], v154
	ds_read_b128 v[178:181], v154 offset:1024
	ds_read_b128 v[182:185], v154 offset:2048
	ds_read_b128 v[186:189], v154 offset:3072
	s_add_u32 s8, s38, 0xfffc0080
	s_addc_u32 s9, s39, -1
	s_cmp_eq_u32 s65, 12
	s_cselect_b32 s41, s27, s9
	s_cselect_b32 s40, s37, s8
	s_cselect_b32 s9, s25, s64
	s_cselect_b32 s8, s60, s61
	v_lshl_add_u64 v[156:157], s[38:39], 0, v[136:137]
	s_add_i32 m0, s4, 0xc000
	ds_read_b128 v[190:193], v155
	ds_read_b128 v[198:201], v155 offset:1024
	ds_read_b128 v[202:205], v155 offset:2048
	ds_read_b128 v[206:209], v155 offset:3072
	ds_read_b128 v[210:213], v155 offset:4096
	ds_read_b128 v[214:217], v155 offset:5120
	ds_read_b128 v[218:221], v155 offset:6144
	ds_read_b128 v[222:225], v155 offset:7168
	global_load_lds_dwordx4 v[156:157], off
	v_lshl_add_u64 v[156:157], s[38:39], 0, v[138:139]
	s_add_i32 m0, s4, 0xe000
	s_nop 0
	global_load_lds_dwordx4 v[156:157], off
	s_waitcnt vmcnt(8)
	s_waitcnt lgkmcnt(0)
	s_barrier
	s_setprio 1
	s_waitcnt lgkmcnt(0)
	v_mfma_f32_16x16x32_bf16 v[124:127], v[144:147], v[190:193], v[124:127]
	v_mfma_f32_16x16x32_bf16 v[120:123], v[166:169], v[190:193], v[120:123]
	v_mfma_f32_16x16x32_bf16 v[108:111], v[144:147], v[202:205], v[108:111]
	v_mfma_f32_16x16x32_bf16 v[104:107], v[166:169], v[202:205], v[104:107]
	v_mfma_f32_16x16x32_bf16 v[92:95], v[144:147], v[210:213], v[92:95]
	v_mfma_f32_16x16x32_bf16 v[88:91], v[166:169], v[210:213], v[88:91]
	v_mfma_f32_16x16x32_bf16 v[76:79], v[144:147], v[218:221], v[76:79]
	v_mfma_f32_16x16x32_bf16 v[72:75], v[166:169], v[218:221], v[72:75]
	v_mfma_f32_16x16x32_bf16 v[124:127], v[162:165], v[198:201], v[124:127]
	v_mfma_f32_16x16x32_bf16 v[120:123], v[170:173], v[198:201], v[120:123]
	v_mfma_f32_16x16x32_bf16 v[108:111], v[162:165], v[206:209], v[108:111]
	v_mfma_f32_16x16x32_bf16 v[104:107], v[170:173], v[206:209], v[104:107]
	v_mfma_f32_16x16x32_bf16 v[92:95], v[162:165], v[214:217], v[92:95]
	v_mfma_f32_16x16x32_bf16 v[88:91], v[170:173], v[214:217], v[88:91]
	v_mfma_f32_16x16x32_bf16 v[76:79], v[162:165], v[222:225], v[76:79]
	v_mfma_f32_16x16x32_bf16 v[72:75], v[170:173], v[222:225], v[72:75]
	s_setprio 0
	s_setprio 1
	v_mfma_f32_16x16x32_bf16 v[116:119], v[174:177], v[190:193], v[116:119]
	v_mfma_f32_16x16x32_bf16 v[112:115], v[182:185], v[190:193], v[112:115]
	v_mfma_f32_16x16x32_bf16 v[100:103], v[174:177], v[202:205], v[100:103]
	v_mfma_f32_16x16x32_bf16 v[96:99], v[182:185], v[202:205], v[96:99]
	v_mfma_f32_16x16x32_bf16 v[84:87], v[174:177], v[210:213], v[84:87]
	v_mfma_f32_16x16x32_bf16 v[80:83], v[182:185], v[210:213], v[80:83]
	v_mfma_f32_16x16x32_bf16 v[68:71], v[174:177], v[218:221], v[68:71]
	v_mfma_f32_16x16x32_bf16 v[64:67], v[182:185], v[218:221], v[64:67]
	v_mfma_f32_16x16x32_bf16 v[116:119], v[178:181], v[198:201], v[116:119]
	v_mfma_f32_16x16x32_bf16 v[112:115], v[186:189], v[198:201], v[112:115]
	v_mfma_f32_16x16x32_bf16 v[100:103], v[178:181], v[206:209], v[100:103]
	v_mfma_f32_16x16x32_bf16 v[96:99], v[186:189], v[206:209], v[96:99]
	v_mfma_f32_16x16x32_bf16 v[84:87], v[178:181], v[214:217], v[84:87]
	v_mfma_f32_16x16x32_bf16 v[80:83], v[186:189], v[214:217], v[80:83]
	v_mfma_f32_16x16x32_bf16 v[68:71], v[178:181], v[222:225], v[68:71]
	v_mfma_f32_16x16x32_bf16 v[64:67], v[186:189], v[222:225], v[64:67]
	s_setprio 0
	s_barrier
	s_add_i32 s66, s55, s3
	v_lshl_add_u64 v[156:157], s[8:9], 0, v[130:131]
	s_mov_b32 m0, s66
	ds_read_b128 v[190:193], v155 offset:16384
	ds_read_b128 v[198:201], v155 offset:17408
	ds_read_b128 v[202:205], v155 offset:18432
	ds_read_b128 v[206:209], v155 offset:19456
	ds_read_b128 v[210:213], v155 offset:20480
	ds_read_b128 v[214:217], v155 offset:21504
	ds_read_b128 v[218:221], v155 offset:22528
	ds_read_b128 v[222:225], v155 offset:23552
	global_load_lds_dwordx4 v[156:157], off
	s_add_i32 m0, s66, 0x2000
	s_add_u32 s66, s8, 0x40000
	v_lshl_add_u64 v[226:227], s[8:9], 0, v[134:135]
	s_addc_u32 s67, s9, 0
	s_add_i32 s73, s58, s3
	global_load_lds_dwordx4 v[226:227], off
	v_lshl_add_u64 v[228:229], s[66:67], 0, v[130:131]
	s_mov_b32 m0, s73
	v_lshl_add_u64 v[230:231], s[40:41], 0, v[132:133]
	global_load_lds_dwordx4 v[228:229], off
	v_lshl_add_u64 v[228:229], s[66:67], 0, v[134:135]
	s_add_i32 m0, s73, 0x2000
	s_nop 0
	global_load_lds_dwordx4 v[228:229], off
	v_lshl_add_u64 v[228:229], s[40:41], 0, v[128:129]
	s_mov_b32 m0, s4
	s_nop 0
	global_load_lds_dwordx4 v[228:229], off
	s_mov_b32 m0, s5
	s_nop 0
	global_load_lds_dwordx4 v[230:231], off
	s_waitcnt vmcnt(8)
	s_waitcnt lgkmcnt(0)
	s_barrier
	s_setprio 1
	s_waitcnt lgkmcnt(0)
	v_mfma_f32_16x16x32_bf16 v[60:63], v[144:147], v[190:193], v[60:63]
	v_mfma_f32_16x16x32_bf16 v[56:59], v[166:169], v[190:193], v[56:59]
	v_mfma_f32_16x16x32_bf16 v[44:47], v[144:147], v[202:205], v[44:47]
	v_mfma_f32_16x16x32_bf16 v[40:43], v[166:169], v[202:205], v[40:43]
	v_mfma_f32_16x16x32_bf16 v[28:31], v[144:147], v[210:213], v[28:31]
	v_mfma_f32_16x16x32_bf16 v[24:27], v[166:169], v[210:213], v[24:27]
	v_mfma_f32_16x16x32_bf16 v[12:15], v[144:147], v[218:221], v[12:15]
	v_mfma_f32_16x16x32_bf16 v[8:11], v[166:169], v[218:221], v[8:11]
	v_mfma_f32_16x16x32_bf16 v[60:63], v[162:165], v[198:201], v[60:63]
	v_mfma_f32_16x16x32_bf16 v[56:59], v[170:173], v[198:201], v[56:59]
	v_mfma_f32_16x16x32_bf16 v[44:47], v[162:165], v[206:209], v[44:47]
	v_mfma_f32_16x16x32_bf16 v[40:43], v[170:173], v[206:209], v[40:43]
	v_mfma_f32_16x16x32_bf16 v[28:31], v[162:165], v[214:217], v[28:31]
	v_mfma_f32_16x16x32_bf16 v[24:27], v[170:173], v[214:217], v[24:27]
	v_mfma_f32_16x16x32_bf16 v[12:15], v[162:165], v[222:225], v[12:15]
	v_mfma_f32_16x16x32_bf16 v[8:11], v[170:173], v[222:225], v[8:11]
	s_setprio 0
	s_setprio 1
	v_mfma_f32_16x16x32_bf16 v[52:55], v[174:177], v[190:193], v[52:55]
	v_mfma_f32_16x16x32_bf16 v[48:51], v[182:185], v[190:193], v[48:51]
	v_mfma_f32_16x16x32_bf16 v[36:39], v[174:177], v[202:205], v[36:39]
	v_mfma_f32_16x16x32_bf16 v[32:35], v[182:185], v[202:205], v[32:35]
	v_mfma_f32_16x16x32_bf16 v[20:23], v[174:177], v[210:213], v[20:23]
	v_mfma_f32_16x16x32_bf16 v[16:19], v[182:185], v[210:213], v[16:19]
	v_mfma_f32_16x16x32_bf16 v[4:7], v[174:177], v[218:221], v[4:7]
	v_mfma_f32_16x16x32_bf16 v[0:3], v[182:185], v[218:221], v[0:3]
	v_mfma_f32_16x16x32_bf16 v[52:55], v[178:181], v[198:201], v[52:55]
	v_mfma_f32_16x16x32_bf16 v[48:51], v[186:189], v[198:201], v[48:51]
	v_mfma_f32_16x16x32_bf16 v[36:39], v[178:181], v[206:209], v[36:39]
	v_mfma_f32_16x16x32_bf16 v[32:35], v[186:189], v[206:209], v[32:35]
	v_mfma_f32_16x16x32_bf16 v[20:23], v[178:181], v[214:217], v[20:23]
	v_mfma_f32_16x16x32_bf16 v[16:19], v[186:189], v[214:217], v[16:19]
	v_mfma_f32_16x16x32_bf16 v[4:7], v[178:181], v[222:225], v[4:7]
	v_mfma_f32_16x16x32_bf16 v[0:3], v[186:189], v[222:225], v[0:3]
	s_setprio 0
	s_barrier
	s_add_i32 s66, 0, 0x18000
	v_add_u32_e32 v158, s66, v149
	s_add_i32 s67, 0, 0x1c000
	ds_read_b128 v[144:147], v158
	ds_read_b128 v[162:165], v158 offset:1024
	ds_read_b128 v[166:169], v158 offset:2048
	ds_read_b128 v[170:173], v158 offset:3072
	v_add_u32_e32 v158, s67, v149
	ds_read_b128 v[174:177], v158
	ds_read_b128 v[178:181], v158 offset:1024
	ds_read_b128 v[182:185], v158 offset:2048
	ds_read_b128 v[186:189], v158 offset:3072
	s_add_u32 s40, s40, 0x40000
	s_addc_u32 s41, s41, 0
	s_mov_b32 m0, s16
	v_lshl_add_u64 v[232:233], s[40:41], 0, v[128:129]
	ds_read_b128 v[190:193], v155 offset:32768
	ds_read_b128 v[198:201], v155 offset:33792
	ds_read_b128 v[202:205], v155 offset:34816
	ds_read_b128 v[206:209], v155 offset:35840
	ds_read_b128 v[210:213], v155 offset:36864
	ds_read_b128 v[214:217], v155 offset:37888
	ds_read_b128 v[218:221], v155 offset:38912
	ds_read_b128 v[222:225], v155 offset:39936
	global_load_lds_dwordx4 v[232:233], off
	v_lshl_add_u64 v[232:233], s[40:41], 0, v[132:133]
	s_mov_b32 m0, s17
	s_nop 0
	global_load_lds_dwordx4 v[232:233], off
	s_waitcnt vmcnt(8)
	s_waitcnt lgkmcnt(0)
	s_barrier
	s_setprio 1
	s_waitcnt lgkmcnt(0)
	v_mfma_f32_16x16x32_bf16 v[124:127], v[144:147], v[190:193], v[124:127]
	v_mfma_f32_16x16x32_bf16 v[120:123], v[166:169], v[190:193], v[120:123]
	v_mfma_f32_16x16x32_bf16 v[108:111], v[144:147], v[202:205], v[108:111]
	v_mfma_f32_16x16x32_bf16 v[104:107], v[166:169], v[202:205], v[104:107]
	v_mfma_f32_16x16x32_bf16 v[92:95], v[144:147], v[210:213], v[92:95]
	v_mfma_f32_16x16x32_bf16 v[88:91], v[166:169], v[210:213], v[88:91]
	v_mfma_f32_16x16x32_bf16 v[76:79], v[144:147], v[218:221], v[76:79]
	v_mfma_f32_16x16x32_bf16 v[72:75], v[166:169], v[218:221], v[72:75]
	v_mfma_f32_16x16x32_bf16 v[124:127], v[162:165], v[198:201], v[124:127]
	v_mfma_f32_16x16x32_bf16 v[120:123], v[170:173], v[198:201], v[120:123]
	v_mfma_f32_16x16x32_bf16 v[108:111], v[162:165], v[206:209], v[108:111]
	v_mfma_f32_16x16x32_bf16 v[104:107], v[170:173], v[206:209], v[104:107]
	v_mfma_f32_16x16x32_bf16 v[92:95], v[162:165], v[214:217], v[92:95]
	v_mfma_f32_16x16x32_bf16 v[88:91], v[170:173], v[214:217], v[88:91]
	v_mfma_f32_16x16x32_bf16 v[76:79], v[162:165], v[222:225], v[76:79]
	v_mfma_f32_16x16x32_bf16 v[72:75], v[170:173], v[222:225], v[72:75]
	s_setprio 0
	s_setprio 1
	v_mfma_f32_16x16x32_bf16 v[116:119], v[174:177], v[190:193], v[116:119]
	v_mfma_f32_16x16x32_bf16 v[112:115], v[182:185], v[190:193], v[112:115]
	v_mfma_f32_16x16x32_bf16 v[100:103], v[174:177], v[202:205], v[100:103]
	v_mfma_f32_16x16x32_bf16 v[96:99], v[182:185], v[202:205], v[96:99]
	v_mfma_f32_16x16x32_bf16 v[84:87], v[174:177], v[210:213], v[84:87]
	v_mfma_f32_16x16x32_bf16 v[80:83], v[182:185], v[210:213], v[80:83]
	v_mfma_f32_16x16x32_bf16 v[68:71], v[174:177], v[218:221], v[68:71]
	v_mfma_f32_16x16x32_bf16 v[64:67], v[182:185], v[218:221], v[64:67]
	v_mfma_f32_16x16x32_bf16 v[116:119], v[178:181], v[198:201], v[116:119]
	v_mfma_f32_16x16x32_bf16 v[112:115], v[186:189], v[198:201], v[112:115]
	v_mfma_f32_16x16x32_bf16 v[100:103], v[178:181], v[206:209], v[100:103]
	v_mfma_f32_16x16x32_bf16 v[96:99], v[186:189], v[206:209], v[96:99]
	v_mfma_f32_16x16x32_bf16 v[84:87], v[178:181], v[214:217], v[84:87]
	v_mfma_f32_16x16x32_bf16 v[80:83], v[186:189], v[214:217], v[80:83]
	v_mfma_f32_16x16x32_bf16 v[68:71], v[178:181], v[222:225], v[68:71]
	v_mfma_f32_16x16x32_bf16 v[64:67], v[186:189], v[222:225], v[64:67]
	s_setprio 0
	s_barrier
	s_add_i32 s40, s66, s3
	v_lshl_add_u64 v[156:157], v[156:157], 0, s[12:13]
	s_mov_b32 m0, s40
	ds_read_b128 v[190:193], v155 offset:49152
	ds_read_b128 v[198:201], v155 offset:50176
	ds_read_b128 v[202:205], v155 offset:51200
	ds_read_b128 v[206:209], v155 offset:52224
	ds_read_b128 v[210:213], v155 offset:53248
	ds_read_b128 v[214:217], v155 offset:54272
	ds_read_b128 v[218:221], v155 offset:55296
	ds_read_b128 v[222:225], v155 offset:56320
	global_load_lds_dwordx4 v[156:157], off
	s_add_i32 m0, s40, 0x2000
	s_add_u32 s8, s8, 0x40080
	v_lshl_add_u64 v[156:157], v[226:227], 0, s[12:13]
	s_addc_u32 s9, s9, 0
	s_add_i32 s40, s67, s3
	global_load_lds_dwordx4 v[156:157], off
	v_lshl_add_u64 v[156:157], s[8:9], 0, v[130:131]
	s_mov_b32 m0, s40
	s_nop 0
	global_load_lds_dwordx4 v[156:157], off
	v_lshl_add_u64 v[156:157], s[8:9], 0, v[134:135]
	s_add_i32 m0, s40, 0x2000
	s_nop 0
	global_load_lds_dwordx4 v[156:157], off
	v_lshl_add_u64 v[156:157], v[228:229], 0, s[12:13]
	s_mov_b32 m0, s19
	s_nop 0
	global_load_lds_dwordx4 v[156:157], off
	v_lshl_add_u64 v[156:157], v[230:231], 0, s[12:13]
	s_mov_b32 m0, s33
	s_nop 0
	global_load_lds_dwordx4 v[156:157], off
	s_waitcnt vmcnt(8)
	s_waitcnt lgkmcnt(0)
	s_barrier
	s_setprio 1
	s_waitcnt lgkmcnt(0)
	v_mfma_f32_16x16x32_bf16 v[60:63], v[144:147], v[190:193], v[60:63]
	s_add_i32 s65, s65, 2
	v_mfma_f32_16x16x32_bf16 v[56:59], v[166:169], v[190:193], v[56:59]
	s_add_u32 s38, s38, 0x100
	v_mfma_f32_16x16x32_bf16 v[44:47], v[144:147], v[202:205], v[44:47]
	s_addc_u32 s39, s39, 0
	v_mfma_f32_16x16x32_bf16 v[40:43], v[166:169], v[202:205], v[40:43]
	s_add_u32 s61, s61, 0x100
	v_mfma_f32_16x16x32_bf16 v[28:31], v[144:147], v[210:213], v[28:31]
	s_addc_u32 s64, s64, 0
	v_mfma_f32_16x16x32_bf16 v[24:27], v[166:169], v[210:213], v[24:27]
	s_cmp_gt_u32 s65, 13
	v_mfma_f32_16x16x32_bf16 v[12:15], v[144:147], v[218:221], v[12:15]
	v_mfma_f32_16x16x32_bf16 v[8:11], v[166:169], v[218:221], v[8:11]
	v_mfma_f32_16x16x32_bf16 v[60:63], v[162:165], v[198:201], v[60:63]
	v_mfma_f32_16x16x32_bf16 v[56:59], v[170:173], v[198:201], v[56:59]
	v_mfma_f32_16x16x32_bf16 v[44:47], v[162:165], v[206:209], v[44:47]
	v_mfma_f32_16x16x32_bf16 v[40:43], v[170:173], v[206:209], v[40:43]
	v_mfma_f32_16x16x32_bf16 v[28:31], v[162:165], v[214:217], v[28:31]
	v_mfma_f32_16x16x32_bf16 v[24:27], v[170:173], v[214:217], v[24:27]
	v_mfma_f32_16x16x32_bf16 v[12:15], v[162:165], v[222:225], v[12:15]
	v_mfma_f32_16x16x32_bf16 v[8:11], v[170:173], v[222:225], v[8:11]
	s_setprio 0
	s_setprio 1
	v_mfma_f32_16x16x32_bf16 v[52:55], v[174:177], v[190:193], v[52:55]
	v_mfma_f32_16x16x32_bf16 v[48:51], v[182:185], v[190:193], v[48:51]
	v_mfma_f32_16x16x32_bf16 v[36:39], v[174:177], v[202:205], v[36:39]
	v_mfma_f32_16x16x32_bf16 v[32:35], v[182:185], v[202:205], v[32:35]
	v_mfma_f32_16x16x32_bf16 v[20:23], v[174:177], v[210:213], v[20:23]
	v_mfma_f32_16x16x32_bf16 v[16:19], v[182:185], v[210:213], v[16:19]
	v_mfma_f32_16x16x32_bf16 v[4:7], v[174:177], v[218:221], v[4:7]
	v_mfma_f32_16x16x32_bf16 v[0:3], v[182:185], v[218:221], v[0:3]
	v_mfma_f32_16x16x32_bf16 v[52:55], v[178:181], v[198:201], v[52:55]
	v_mfma_f32_16x16x32_bf16 v[48:51], v[186:189], v[198:201], v[48:51]
	v_mfma_f32_16x16x32_bf16 v[36:39], v[178:181], v[206:209], v[36:39]
	v_mfma_f32_16x16x32_bf16 v[32:35], v[186:189], v[206:209], v[32:35]
	v_mfma_f32_16x16x32_bf16 v[20:23], v[178:181], v[214:217], v[20:23]
	v_mfma_f32_16x16x32_bf16 v[16:19], v[186:189], v[214:217], v[16:19]
	v_mfma_f32_16x16x32_bf16 v[4:7], v[178:181], v[222:225], v[4:7]
	v_mfma_f32_16x16x32_bf16 v[0:3], v[186:189], v[222:225], v[0:3]
	s_setprio 0
	s_barrier
	s_cbranch_scc0 .LBB0_666
	s_and_b64 vcc, exec, s[14:15]
	s_cbranch_vccz .LBB0_669
	s_barrier

.LBB0_765:
	ds_read_b128 v[144:147], v154
	ds_read_b128 v[162:165], v154 offset:1024
	ds_read_b128 v[166:169], v154 offset:2048
	ds_read_b128 v[170:173], v154 offset:3072
	ds_read_b128 v[174:177], v155
	ds_read_b128 v[178:181], v155 offset:1024
	ds_read_b128 v[182:185], v155 offset:2048
	ds_read_b128 v[186:189], v155 offset:3072
	s_add_u32 s8, s30, 0xfffc0080
	s_addc_u32 s9, s31, -1
	s_cmp_eq_u32 s60, 12
	s_cselect_b32 s37, s15, s9
	s_cselect_b32 s36, s47, s8
	s_cselect_b32 s9, s13, s59
	s_cselect_b32 s8, s55, s58
	v_lshl_add_u64 v[148:149], s[30:31], 0, v[136:137]
	s_add_i32 m0, s4, 0xc000
	ds_read_b128 v[190:193], v156
	ds_read_b128 v[198:201], v156 offset:1024
	ds_read_b128 v[202:205], v156 offset:2048
	ds_read_b128 v[206:209], v156 offset:3072
	ds_read_b128 v[210:213], v156 offset:4096
	ds_read_b128 v[214:217], v156 offset:5120
	ds_read_b128 v[218:221], v156 offset:6144
	ds_read_b128 v[222:225], v156 offset:7168
	global_load_lds_dwordx4 v[148:149], off
	v_lshl_add_u64 v[148:149], s[30:31], 0, v[138:139]
	s_add_i32 m0, s4, 0xe000
	s_nop 0
	global_load_lds_dwordx4 v[148:149], off
	s_waitcnt vmcnt(8)
	s_waitcnt lgkmcnt(0)
	s_barrier
	s_setprio 1
	s_waitcnt lgkmcnt(0)
	v_mfma_f32_16x16x32_bf16 v[124:127], v[144:147], v[190:193], v[124:127]
	v_mfma_f32_16x16x32_bf16 v[120:123], v[166:169], v[190:193], v[120:123]
	v_mfma_f32_16x16x32_bf16 v[108:111], v[144:147], v[202:205], v[108:111]
	v_mfma_f32_16x16x32_bf16 v[104:107], v[166:169], v[202:205], v[104:107]
	v_mfma_f32_16x16x32_bf16 v[92:95], v[144:147], v[210:213], v[92:95]
	v_mfma_f32_16x16x32_bf16 v[88:91], v[166:169], v[210:213], v[88:91]
	v_mfma_f32_16x16x32_bf16 v[76:79], v[144:147], v[218:221], v[76:79]
	v_mfma_f32_16x16x32_bf16 v[72:75], v[166:169], v[218:221], v[72:75]
	v_mfma_f32_16x16x32_bf16 v[124:127], v[162:165], v[198:201], v[124:127]
	v_mfma_f32_16x16x32_bf16 v[120:123], v[170:173], v[198:201], v[120:123]
	v_mfma_f32_16x16x32_bf16 v[108:111], v[162:165], v[206:209], v[108:111]
	v_mfma_f32_16x16x32_bf16 v[104:107], v[170:173], v[206:209], v[104:107]
	v_mfma_f32_16x16x32_bf16 v[92:95], v[162:165], v[214:217], v[92:95]
	v_mfma_f32_16x16x32_bf16 v[88:91], v[170:173], v[214:217], v[88:91]
	v_mfma_f32_16x16x32_bf16 v[76:79], v[162:165], v[222:225], v[76:79]
	v_mfma_f32_16x16x32_bf16 v[72:75], v[170:173], v[222:225], v[72:75]
	s_setprio 0
	s_setprio 1
	v_mfma_f32_16x16x32_bf16 v[116:119], v[174:177], v[190:193], v[116:119]
	v_mfma_f32_16x16x32_bf16 v[112:115], v[182:185], v[190:193], v[112:115]
	v_mfma_f32_16x16x32_bf16 v[100:103], v[174:177], v[202:205], v[100:103]
	v_mfma_f32_16x16x32_bf16 v[96:99], v[182:185], v[202:205], v[96:99]
	v_mfma_f32_16x16x32_bf16 v[84:87], v[174:177], v[210:213], v[84:87]
	v_mfma_f32_16x16x32_bf16 v[80:83], v[182:185], v[210:213], v[80:83]
	v_mfma_f32_16x16x32_bf16 v[68:71], v[174:177], v[218:221], v[68:71]
	v_mfma_f32_16x16x32_bf16 v[64:67], v[182:185], v[218:221], v[64:67]
	v_mfma_f32_16x16x32_bf16 v[116:119], v[178:181], v[198:201], v[116:119]
	v_mfma_f32_16x16x32_bf16 v[112:115], v[186:189], v[198:201], v[112:115]
	v_mfma_f32_16x16x32_bf16 v[100:103], v[178:181], v[206:209], v[100:103]
	v_mfma_f32_16x16x32_bf16 v[96:99], v[186:189], v[206:209], v[96:99]
	v_mfma_f32_16x16x32_bf16 v[84:87], v[178:181], v[214:217], v[84:87]
	v_mfma_f32_16x16x32_bf16 v[80:83], v[186:189], v[214:217], v[80:83]
	v_mfma_f32_16x16x32_bf16 v[68:71], v[178:181], v[222:225], v[68:71]
	v_mfma_f32_16x16x32_bf16 v[64:67], v[186:189], v[222:225], v[64:67]
	s_setprio 0
	s_barrier
	s_add_i32 s61, s38, s3
	v_lshl_add_u64 v[148:149], s[8:9], 0, v[132:133]
	s_mov_b32 m0, s61
	ds_read_b128 v[190:193], v156 offset:16384
	ds_read_b128 v[198:201], v156 offset:17408
	ds_read_b128 v[202:205], v156 offset:18432
	ds_read_b128 v[206:209], v156 offset:19456
	ds_read_b128 v[210:213], v156 offset:20480
	ds_read_b128 v[214:217], v156 offset:21504
	ds_read_b128 v[218:221], v156 offset:22528
	ds_read_b128 v[222:225], v156 offset:23552
	global_load_lds_dwordx4 v[148:149], off
	s_add_i32 m0, s61, 0x2000
	s_add_u32 s64, s8, 0x40000
	v_lshl_add_u64 v[226:227], s[8:9], 0, v[128:129]
	s_addc_u32 s65, s9, 0
	s_add_i32 s61, s39, s3
	global_load_lds_dwordx4 v[226:227], off
	v_lshl_add_u64 v[228:229], s[64:65], 0, v[132:133]
	s_mov_b32 m0, s61
	v_lshl_add_u64 v[230:231], s[36:37], 0, v[130:131]
	global_load_lds_dwordx4 v[228:229], off
	v_lshl_add_u64 v[228:229], s[64:65], 0, v[128:129]
	s_add_i32 m0, s61, 0x2000
	s_nop 0
	global_load_lds_dwordx4 v[228:229], off
	v_lshl_add_u64 v[228:229], s[36:37], 0, v[134:135]
	s_mov_b32 m0, s4
	s_nop 0
	global_load_lds_dwordx4 v[228:229], off
	s_mov_b32 m0, s5
	s_nop 0
	global_load_lds_dwordx4 v[230:231], off
	s_waitcnt vmcnt(8)
	s_waitcnt lgkmcnt(0)
	s_barrier
	s_setprio 1
	s_waitcnt lgkmcnt(0)
	v_mfma_f32_16x16x32_bf16 v[60:63], v[144:147], v[190:193], v[60:63]
	v_mfma_f32_16x16x32_bf16 v[56:59], v[166:169], v[190:193], v[56:59]
	v_mfma_f32_16x16x32_bf16 v[44:47], v[144:147], v[202:205], v[44:47]
	v_mfma_f32_16x16x32_bf16 v[40:43], v[166:169], v[202:205], v[40:43]
	v_mfma_f32_16x16x32_bf16 v[28:31], v[144:147], v[210:213], v[28:31]
	v_mfma_f32_16x16x32_bf16 v[24:27], v[166:169], v[210:213], v[24:27]
	v_mfma_f32_16x16x32_bf16 v[12:15], v[144:147], v[218:221], v[12:15]
	v_mfma_f32_16x16x32_bf16 v[8:11], v[166:169], v[218:221], v[8:11]
	v_mfma_f32_16x16x32_bf16 v[60:63], v[162:165], v[198:201], v[60:63]
	v_mfma_f32_16x16x32_bf16 v[56:59], v[170:173], v[198:201], v[56:59]
	v_mfma_f32_16x16x32_bf16 v[44:47], v[162:165], v[206:209], v[44:47]
	v_mfma_f32_16x16x32_bf16 v[40:43], v[170:173], v[206:209], v[40:43]
	v_mfma_f32_16x16x32_bf16 v[28:31], v[162:165], v[214:217], v[28:31]
	v_mfma_f32_16x16x32_bf16 v[24:27], v[170:173], v[214:217], v[24:27]
	v_mfma_f32_16x16x32_bf16 v[12:15], v[162:165], v[222:225], v[12:15]
	v_mfma_f32_16x16x32_bf16 v[8:11], v[170:173], v[222:225], v[8:11]
	s_setprio 0
	s_setprio 1
	v_mfma_f32_16x16x32_bf16 v[52:55], v[174:177], v[190:193], v[52:55]
	v_mfma_f32_16x16x32_bf16 v[48:51], v[182:185], v[190:193], v[48:51]
	v_mfma_f32_16x16x32_bf16 v[36:39], v[174:177], v[202:205], v[36:39]
	v_mfma_f32_16x16x32_bf16 v[32:35], v[182:185], v[202:205], v[32:35]
	v_mfma_f32_16x16x32_bf16 v[20:23], v[174:177], v[210:213], v[20:23]
	v_mfma_f32_16x16x32_bf16 v[16:19], v[182:185], v[210:213], v[16:19]
	v_mfma_f32_16x16x32_bf16 v[4:7], v[174:177], v[218:221], v[4:7]
	v_mfma_f32_16x16x32_bf16 v[0:3], v[182:185], v[218:221], v[0:3]
	v_mfma_f32_16x16x32_bf16 v[52:55], v[178:181], v[198:201], v[52:55]
	v_mfma_f32_16x16x32_bf16 v[48:51], v[186:189], v[198:201], v[48:51]
	v_mfma_f32_16x16x32_bf16 v[36:39], v[178:181], v[206:209], v[36:39]
	v_mfma_f32_16x16x32_bf16 v[32:35], v[186:189], v[206:209], v[32:35]
	v_mfma_f32_16x16x32_bf16 v[20:23], v[178:181], v[214:217], v[20:23]
	v_mfma_f32_16x16x32_bf16 v[16:19], v[186:189], v[214:217], v[16:19]
	v_mfma_f32_16x16x32_bf16 v[4:7], v[178:181], v[222:225], v[4:7]
	v_mfma_f32_16x16x32_bf16 v[0:3], v[186:189], v[222:225], v[0:3]
	s_setprio 0
	s_barrier
	s_add_i32 s61, 0, 0x18000
	v_add_u32_e32 v157, s61, v151
	s_add_i32 s64, 0, 0x1c000
	ds_read_b128 v[144:147], v157
	ds_read_b128 v[162:165], v157 offset:1024
	ds_read_b128 v[166:169], v157 offset:2048
	ds_read_b128 v[170:173], v157 offset:3072
	v_add_u32_e32 v157, s64, v151
	ds_read_b128 v[174:177], v157
	ds_read_b128 v[178:181], v157 offset:1024
	ds_read_b128 v[182:185], v157 offset:2048
	ds_read_b128 v[186:189], v157 offset:3072
	s_add_u32 s36, s36, 0x40000
	s_addc_u32 s37, s37, 0
	s_mov_b32 m0, s16
	v_lshl_add_u64 v[232:233], s[36:37], 0, v[134:135]
	ds_read_b128 v[190:193], v156 offset:32768
	ds_read_b128 v[198:201], v156 offset:33792
	ds_read_b128 v[202:205], v156 offset:34816
	ds_read_b128 v[206:209], v156 offset:35840
	ds_read_b128 v[210:213], v156 offset:36864
	ds_read_b128 v[214:217], v156 offset:37888
	ds_read_b128 v[218:221], v156 offset:38912
	ds_read_b128 v[222:225], v156 offset:39936
	global_load_lds_dwordx4 v[232:233], off
	v_lshl_add_u64 v[232:233], s[36:37], 0, v[130:131]
	s_mov_b32 m0, s17
	s_nop 0
	global_load_lds_dwordx4 v[232:233], off
	s_waitcnt vmcnt(8)
	s_waitcnt lgkmcnt(0)
	s_barrier
	s_setprio 1
	s_waitcnt lgkmcnt(0)
	v_mfma_f32_16x16x32_bf16 v[124:127], v[144:147], v[190:193], v[124:127]
	v_mfma_f32_16x16x32_bf16 v[120:123], v[166:169], v[190:193], v[120:123]
	v_mfma_f32_16x16x32_bf16 v[108:111], v[144:147], v[202:205], v[108:111]
	v_mfma_f32_16x16x32_bf16 v[104:107], v[166:169], v[202:205], v[104:107]
	v_mfma_f32_16x16x32_bf16 v[92:95], v[144:147], v[210:213], v[92:95]
	v_mfma_f32_16x16x32_bf16 v[88:91], v[166:169], v[210:213], v[88:91]
	v_mfma_f32_16x16x32_bf16 v[76:79], v[144:147], v[218:221], v[76:79]
	v_mfma_f32_16x16x32_bf16 v[72:75], v[166:169], v[218:221], v[72:75]
	v_mfma_f32_16x16x32_bf16 v[124:127], v[162:165], v[198:201], v[124:127]
	v_mfma_f32_16x16x32_bf16 v[120:123], v[170:173], v[198:201], v[120:123]
	v_mfma_f32_16x16x32_bf16 v[108:111], v[162:165], v[206:209], v[108:111]
	v_mfma_f32_16x16x32_bf16 v[104:107], v[170:173], v[206:209], v[104:107]
	v_mfma_f32_16x16x32_bf16 v[92:95], v[162:165], v[214:217], v[92:95]
	v_mfma_f32_16x16x32_bf16 v[88:91], v[170:173], v[214:217], v[88:91]
	v_mfma_f32_16x16x32_bf16 v[76:79], v[162:165], v[222:225], v[76:79]
	v_mfma_f32_16x16x32_bf16 v[72:75], v[170:173], v[222:225], v[72:75]
	s_setprio 0
	s_setprio 1
	v_mfma_f32_16x16x32_bf16 v[116:119], v[174:177], v[190:193], v[116:119]
	v_mfma_f32_16x16x32_bf16 v[112:115], v[182:185], v[190:193], v[112:115]
	v_mfma_f32_16x16x32_bf16 v[100:103], v[174:177], v[202:205], v[100:103]
	v_mfma_f32_16x16x32_bf16 v[96:99], v[182:185], v[202:205], v[96:99]
	v_mfma_f32_16x16x32_bf16 v[84:87], v[174:177], v[210:213], v[84:87]
	v_mfma_f32_16x16x32_bf16 v[80:83], v[182:185], v[210:213], v[80:83]
	v_mfma_f32_16x16x32_bf16 v[68:71], v[174:177], v[218:221], v[68:71]
	v_mfma_f32_16x16x32_bf16 v[64:67], v[182:185], v[218:221], v[64:67]
	v_mfma_f32_16x16x32_bf16 v[116:119], v[178:181], v[198:201], v[116:119]
	v_mfma_f32_16x16x32_bf16 v[112:115], v[186:189], v[198:201], v[112:115]
	v_mfma_f32_16x16x32_bf16 v[100:103], v[178:181], v[206:209], v[100:103]
	v_mfma_f32_16x16x32_bf16 v[96:99], v[186:189], v[206:209], v[96:99]
	v_mfma_f32_16x16x32_bf16 v[84:87], v[178:181], v[214:217], v[84:87]
	v_mfma_f32_16x16x32_bf16 v[80:83], v[186:189], v[214:217], v[80:83]
	v_mfma_f32_16x16x32_bf16 v[68:71], v[178:181], v[222:225], v[68:71]
	v_mfma_f32_16x16x32_bf16 v[64:67], v[186:189], v[222:225], v[64:67]
	s_setprio 0
	s_barrier
	s_add_i32 s36, s61, s3
	v_lshl_add_u64 v[148:149], v[148:149], 0, s[6:7]
	s_mov_b32 m0, s36
	ds_read_b128 v[190:193], v156 offset:49152
	ds_read_b128 v[198:201], v156 offset:50176
	ds_read_b128 v[202:205], v156 offset:51200
	ds_read_b128 v[206:209], v156 offset:52224
	ds_read_b128 v[210:213], v156 offset:53248
	ds_read_b128 v[214:217], v156 offset:54272
	ds_read_b128 v[218:221], v156 offset:55296
	ds_read_b128 v[222:225], v156 offset:56320
	global_load_lds_dwordx4 v[148:149], off
	s_add_i32 m0, s36, 0x2000
	s_add_u32 s8, s8, 0x40080
	v_lshl_add_u64 v[148:149], v[226:227], 0, s[6:7]
	s_addc_u32 s9, s9, 0
	s_add_i32 s36, s64, s3
	global_load_lds_dwordx4 v[148:149], off
	v_lshl_add_u64 v[148:149], s[8:9], 0, v[132:133]
	s_mov_b32 m0, s36
	s_nop 0
	global_load_lds_dwordx4 v[148:149], off
	v_lshl_add_u64 v[148:149], s[8:9], 0, v[128:129]
	s_add_i32 m0, s36, 0x2000
	s_nop 0
	global_load_lds_dwordx4 v[148:149], off
	v_lshl_add_u64 v[148:149], v[228:229], 0, s[6:7]
	s_mov_b32 m0, s29
	s_nop 0
	global_load_lds_dwordx4 v[148:149], off
	v_lshl_add_u64 v[148:149], v[230:231], 0, s[6:7]
	s_mov_b32 m0, s33
	s_nop 0
	global_load_lds_dwordx4 v[148:149], off
	s_waitcnt vmcnt(8)
	s_waitcnt lgkmcnt(0)
	s_barrier
	s_setprio 1
	s_waitcnt lgkmcnt(0)
	v_mfma_f32_16x16x32_bf16 v[60:63], v[144:147], v[190:193], v[60:63]
	s_add_i32 s60, s60, 2
	v_mfma_f32_16x16x32_bf16 v[56:59], v[166:169], v[190:193], v[56:59]
	s_add_u32 s30, s30, 0x100
	v_mfma_f32_16x16x32_bf16 v[44:47], v[144:147], v[202:205], v[44:47]
	s_addc_u32 s31, s31, 0
	v_mfma_f32_16x16x32_bf16 v[40:43], v[166:169], v[202:205], v[40:43]
	s_add_u32 s58, s58, 0x100
	v_mfma_f32_16x16x32_bf16 v[28:31], v[144:147], v[210:213], v[28:31]
	s_addc_u32 s59, s59, 0
	v_mfma_f32_16x16x32_bf16 v[24:27], v[166:169], v[210:213], v[24:27]
	s_cmp_gt_u32 s60, 13
	v_mfma_f32_16x16x32_bf16 v[12:15], v[144:147], v[218:221], v[12:15]
	v_mfma_f32_16x16x32_bf16 v[8:11], v[166:169], v[218:221], v[8:11]
	v_mfma_f32_16x16x32_bf16 v[60:63], v[162:165], v[198:201], v[60:63]
	v_mfma_f32_16x16x32_bf16 v[56:59], v[170:173], v[198:201], v[56:59]
	v_mfma_f32_16x16x32_bf16 v[44:47], v[162:165], v[206:209], v[44:47]
	v_mfma_f32_16x16x32_bf16 v[40:43], v[170:173], v[206:209], v[40:43]
	v_mfma_f32_16x16x32_bf16 v[28:31], v[162:165], v[214:217], v[28:31]
	v_mfma_f32_16x16x32_bf16 v[24:27], v[170:173], v[214:217], v[24:27]
	v_mfma_f32_16x16x32_bf16 v[12:15], v[162:165], v[222:225], v[12:15]
	v_mfma_f32_16x16x32_bf16 v[8:11], v[170:173], v[222:225], v[8:11]
	s_setprio 0
	s_setprio 1
	v_mfma_f32_16x16x32_bf16 v[52:55], v[174:177], v[190:193], v[52:55]
	v_mfma_f32_16x16x32_bf16 v[48:51], v[182:185], v[190:193], v[48:51]
	v_mfma_f32_16x16x32_bf16 v[36:39], v[174:177], v[202:205], v[36:39]
	v_mfma_f32_16x16x32_bf16 v[32:35], v[182:185], v[202:205], v[32:35]
	v_mfma_f32_16x16x32_bf16 v[20:23], v[174:177], v[210:213], v[20:23]
	v_mfma_f32_16x16x32_bf16 v[16:19], v[182:185], v[210:213], v[16:19]
	v_mfma_f32_16x16x32_bf16 v[4:7], v[174:177], v[218:221], v[4:7]
	v_mfma_f32_16x16x32_bf16 v[0:3], v[182:185], v[218:221], v[0:3]
	v_mfma_f32_16x16x32_bf16 v[52:55], v[178:181], v[198:201], v[52:55]
	v_mfma_f32_16x16x32_bf16 v[48:51], v[186:189], v[198:201], v[48:51]
	v_mfma_f32_16x16x32_bf16 v[36:39], v[178:181], v[206:209], v[36:39]
	v_mfma_f32_16x16x32_bf16 v[32:35], v[186:189], v[206:209], v[32:35]
	v_mfma_f32_16x16x32_bf16 v[20:23], v[178:181], v[214:217], v[20:23]
	v_mfma_f32_16x16x32_bf16 v[16:19], v[186:189], v[214:217], v[16:19]
	v_mfma_f32_16x16x32_bf16 v[4:7], v[178:181], v[222:225], v[4:7]
	v_mfma_f32_16x16x32_bf16 v[0:3], v[186:189], v[222:225], v[0:3]
	s_setprio 0
	s_barrier
	s_cbranch_scc0 .LBB0_765
	s_and_b64 vcc, exec, s[10:11]
	s_cbranch_vccz .LBB0_768
	s_barrier

.LBB0_841:
	ds_read_b128 v[144:147], v153
	ds_read_b128 v[162:165], v153 offset:1024
	ds_read_b128 v[166:169], v153 offset:2048
	ds_read_b128 v[170:173], v153 offset:3072
	ds_read_b128 v[174:177], v154
	ds_read_b128 v[178:181], v154 offset:1024
	ds_read_b128 v[182:185], v154 offset:2048
	ds_read_b128 v[186:189], v154 offset:3072
	s_add_u32 s8, s36, 0xfff00080
	s_addc_u32 s9, s37, -1
	s_cmp_eq_u32 s65, 60
	s_cselect_b32 s39, s25, s9
	s_cselect_b32 s38, s31, s8
	s_cselect_b32 s9, s21, s64
	s_cselect_b32 s8, s60, s61
	v_lshl_add_u64 v[156:157], s[36:37], 0, v[136:137]
	s_add_i32 m0, s4, 0xc000
	ds_read_b128 v[190:193], v155
	ds_read_b128 v[198:201], v155 offset:1024
	ds_read_b128 v[202:205], v155 offset:2048
	ds_read_b128 v[206:209], v155 offset:3072
	ds_read_b128 v[210:213], v155 offset:4096
	ds_read_b128 v[214:217], v155 offset:5120
	ds_read_b128 v[218:221], v155 offset:6144
	ds_read_b128 v[222:225], v155 offset:7168
	global_load_lds_dwordx4 v[156:157], off
	v_lshl_add_u64 v[156:157], s[36:37], 0, v[138:139]
	s_add_i32 m0, s4, 0xe000
	s_nop 0
	global_load_lds_dwordx4 v[156:157], off
	s_waitcnt vmcnt(8)
	s_waitcnt lgkmcnt(0)
	s_barrier
	s_setprio 1
	s_waitcnt lgkmcnt(0)
	v_mfma_f32_16x16x32_bf16 v[124:127], v[144:147], v[190:193], v[124:127]
	v_mfma_f32_16x16x32_bf16 v[120:123], v[166:169], v[190:193], v[120:123]
	v_mfma_f32_16x16x32_bf16 v[108:111], v[144:147], v[202:205], v[108:111]
	v_mfma_f32_16x16x32_bf16 v[104:107], v[166:169], v[202:205], v[104:107]
	v_mfma_f32_16x16x32_bf16 v[92:95], v[144:147], v[210:213], v[92:95]
	v_mfma_f32_16x16x32_bf16 v[88:91], v[166:169], v[210:213], v[88:91]
	v_mfma_f32_16x16x32_bf16 v[76:79], v[144:147], v[218:221], v[76:79]
	v_mfma_f32_16x16x32_bf16 v[72:75], v[166:169], v[218:221], v[72:75]
	v_mfma_f32_16x16x32_bf16 v[124:127], v[162:165], v[198:201], v[124:127]
	v_mfma_f32_16x16x32_bf16 v[120:123], v[170:173], v[198:201], v[120:123]
	v_mfma_f32_16x16x32_bf16 v[108:111], v[162:165], v[206:209], v[108:111]
	v_mfma_f32_16x16x32_bf16 v[104:107], v[170:173], v[206:209], v[104:107]
	v_mfma_f32_16x16x32_bf16 v[92:95], v[162:165], v[214:217], v[92:95]
	v_mfma_f32_16x16x32_bf16 v[88:91], v[170:173], v[214:217], v[88:91]
	v_mfma_f32_16x16x32_bf16 v[76:79], v[162:165], v[222:225], v[76:79]
	v_mfma_f32_16x16x32_bf16 v[72:75], v[170:173], v[222:225], v[72:75]
	s_setprio 0
	s_setprio 1
	v_mfma_f32_16x16x32_bf16 v[116:119], v[174:177], v[190:193], v[116:119]
	v_mfma_f32_16x16x32_bf16 v[112:115], v[182:185], v[190:193], v[112:115]
	v_mfma_f32_16x16x32_bf16 v[100:103], v[174:177], v[202:205], v[100:103]
	v_mfma_f32_16x16x32_bf16 v[96:99], v[182:185], v[202:205], v[96:99]
	v_mfma_f32_16x16x32_bf16 v[84:87], v[174:177], v[210:213], v[84:87]
	v_mfma_f32_16x16x32_bf16 v[80:83], v[182:185], v[210:213], v[80:83]
	v_mfma_f32_16x16x32_bf16 v[68:71], v[174:177], v[218:221], v[68:71]
	v_mfma_f32_16x16x32_bf16 v[64:67], v[182:185], v[218:221], v[64:67]
	v_mfma_f32_16x16x32_bf16 v[116:119], v[178:181], v[198:201], v[116:119]
	v_mfma_f32_16x16x32_bf16 v[112:115], v[186:189], v[198:201], v[112:115]
	v_mfma_f32_16x16x32_bf16 v[100:103], v[178:181], v[206:209], v[100:103]
	v_mfma_f32_16x16x32_bf16 v[96:99], v[186:189], v[206:209], v[96:99]
	v_mfma_f32_16x16x32_bf16 v[84:87], v[178:181], v[214:217], v[84:87]
	v_mfma_f32_16x16x32_bf16 v[80:83], v[186:189], v[214:217], v[80:83]
	v_mfma_f32_16x16x32_bf16 v[68:71], v[178:181], v[222:225], v[68:71]
	v_mfma_f32_16x16x32_bf16 v[64:67], v[186:189], v[222:225], v[64:67]
	s_setprio 0
	s_barrier
	s_add_i32 s66, s55, s3
	v_lshl_add_u64 v[156:157], s[8:9], 0, v[130:131]
	s_mov_b32 m0, s66
	ds_read_b128 v[190:193], v155 offset:16384
	ds_read_b128 v[198:201], v155 offset:17408
	ds_read_b128 v[202:205], v155 offset:18432
	ds_read_b128 v[206:209], v155 offset:19456
	ds_read_b128 v[210:213], v155 offset:20480
	ds_read_b128 v[214:217], v155 offset:21504
	ds_read_b128 v[218:221], v155 offset:22528
	ds_read_b128 v[222:225], v155 offset:23552
	global_load_lds_dwordx4 v[156:157], off
	s_add_i32 m0, s66, 0x2000
	s_add_u32 s66, s8, 0x100000
	v_lshl_add_u64 v[226:227], s[8:9], 0, v[134:135]
	s_addc_u32 s67, s9, 0
	s_add_i32 s73, s58, s3
	global_load_lds_dwordx4 v[226:227], off
	v_lshl_add_u64 v[228:229], s[66:67], 0, v[130:131]
	s_mov_b32 m0, s73
	v_lshl_add_u64 v[230:231], s[38:39], 0, v[132:133]
	global_load_lds_dwordx4 v[228:229], off
	v_lshl_add_u64 v[228:229], s[66:67], 0, v[134:135]
	s_add_i32 m0, s73, 0x2000
	s_nop 0
	global_load_lds_dwordx4 v[228:229], off
	v_lshl_add_u64 v[228:229], s[38:39], 0, v[128:129]
	s_mov_b32 m0, s4
	s_nop 0
	global_load_lds_dwordx4 v[228:229], off
	s_mov_b32 m0, s5
	s_nop 0
	global_load_lds_dwordx4 v[230:231], off
	s_waitcnt vmcnt(8)
	s_waitcnt lgkmcnt(0)
	s_barrier
	s_setprio 1
	s_waitcnt lgkmcnt(0)
	v_mfma_f32_16x16x32_bf16 v[60:63], v[144:147], v[190:193], v[60:63]
	v_mfma_f32_16x16x32_bf16 v[56:59], v[166:169], v[190:193], v[56:59]
	v_mfma_f32_16x16x32_bf16 v[44:47], v[144:147], v[202:205], v[44:47]
	v_mfma_f32_16x16x32_bf16 v[40:43], v[166:169], v[202:205], v[40:43]
	v_mfma_f32_16x16x32_bf16 v[28:31], v[144:147], v[210:213], v[28:31]
	v_mfma_f32_16x16x32_bf16 v[24:27], v[166:169], v[210:213], v[24:27]
	v_mfma_f32_16x16x32_bf16 v[12:15], v[144:147], v[218:221], v[12:15]
	v_mfma_f32_16x16x32_bf16 v[8:11], v[166:169], v[218:221], v[8:11]
	v_mfma_f32_16x16x32_bf16 v[60:63], v[162:165], v[198:201], v[60:63]
	v_mfma_f32_16x16x32_bf16 v[56:59], v[170:173], v[198:201], v[56:59]
	v_mfma_f32_16x16x32_bf16 v[44:47], v[162:165], v[206:209], v[44:47]
	v_mfma_f32_16x16x32_bf16 v[40:43], v[170:173], v[206:209], v[40:43]
	v_mfma_f32_16x16x32_bf16 v[28:31], v[162:165], v[214:217], v[28:31]
	v_mfma_f32_16x16x32_bf16 v[24:27], v[170:173], v[214:217], v[24:27]
	v_mfma_f32_16x16x32_bf16 v[12:15], v[162:165], v[222:225], v[12:15]
	v_mfma_f32_16x16x32_bf16 v[8:11], v[170:173], v[222:225], v[8:11]
	s_setprio 0
	s_setprio 1
	v_mfma_f32_16x16x32_bf16 v[52:55], v[174:177], v[190:193], v[52:55]
	v_mfma_f32_16x16x32_bf16 v[48:51], v[182:185], v[190:193], v[48:51]
	v_mfma_f32_16x16x32_bf16 v[36:39], v[174:177], v[202:205], v[36:39]
	v_mfma_f32_16x16x32_bf16 v[32:35], v[182:185], v[202:205], v[32:35]
	v_mfma_f32_16x16x32_bf16 v[20:23], v[174:177], v[210:213], v[20:23]
	v_mfma_f32_16x16x32_bf16 v[16:19], v[182:185], v[210:213], v[16:19]
	v_mfma_f32_16x16x32_bf16 v[4:7], v[174:177], v[218:221], v[4:7]
	v_mfma_f32_16x16x32_bf16 v[0:3], v[182:185], v[218:221], v[0:3]
	v_mfma_f32_16x16x32_bf16 v[52:55], v[178:181], v[198:201], v[52:55]
	v_mfma_f32_16x16x32_bf16 v[48:51], v[186:189], v[198:201], v[48:51]
	v_mfma_f32_16x16x32_bf16 v[36:39], v[178:181], v[206:209], v[36:39]
	v_mfma_f32_16x16x32_bf16 v[32:35], v[186:189], v[206:209], v[32:35]
	v_mfma_f32_16x16x32_bf16 v[20:23], v[178:181], v[214:217], v[20:23]
	v_mfma_f32_16x16x32_bf16 v[16:19], v[186:189], v[214:217], v[16:19]
	v_mfma_f32_16x16x32_bf16 v[4:7], v[178:181], v[222:225], v[4:7]
	v_mfma_f32_16x16x32_bf16 v[0:3], v[186:189], v[222:225], v[0:3]
	s_setprio 0
	s_barrier
	s_add_i32 s66, 0, 0x18000
	v_add_u32_e32 v158, s66, v149
	s_add_i32 s67, 0, 0x1c000
	ds_read_b128 v[144:147], v158
	ds_read_b128 v[162:165], v158 offset:1024
	ds_read_b128 v[166:169], v158 offset:2048
	ds_read_b128 v[170:173], v158 offset:3072
	v_add_u32_e32 v158, s67, v149
	ds_read_b128 v[174:177], v158
	ds_read_b128 v[178:181], v158 offset:1024
	ds_read_b128 v[182:185], v158 offset:2048
	ds_read_b128 v[186:189], v158 offset:3072
	s_add_u32 s38, s38, 0x100000
	s_addc_u32 s39, s39, 0
	s_mov_b32 m0, s16
	v_lshl_add_u64 v[232:233], s[38:39], 0, v[128:129]
	ds_read_b128 v[190:193], v155 offset:32768
	ds_read_b128 v[198:201], v155 offset:33792
	ds_read_b128 v[202:205], v155 offset:34816
	ds_read_b128 v[206:209], v155 offset:35840
	ds_read_b128 v[210:213], v155 offset:36864
	ds_read_b128 v[214:217], v155 offset:37888
	ds_read_b128 v[218:221], v155 offset:38912
	ds_read_b128 v[222:225], v155 offset:39936
	global_load_lds_dwordx4 v[232:233], off
	v_lshl_add_u64 v[232:233], s[38:39], 0, v[132:133]
	s_mov_b32 m0, s17
	s_nop 0
	global_load_lds_dwordx4 v[232:233], off
	s_waitcnt vmcnt(8)
	s_waitcnt lgkmcnt(0)
	s_barrier
	s_setprio 1
	s_waitcnt lgkmcnt(0)
	v_mfma_f32_16x16x32_bf16 v[124:127], v[144:147], v[190:193], v[124:127]
	v_mfma_f32_16x16x32_bf16 v[120:123], v[166:169], v[190:193], v[120:123]
	v_mfma_f32_16x16x32_bf16 v[108:111], v[144:147], v[202:205], v[108:111]
	v_mfma_f32_16x16x32_bf16 v[104:107], v[166:169], v[202:205], v[104:107]
	v_mfma_f32_16x16x32_bf16 v[92:95], v[144:147], v[210:213], v[92:95]
	v_mfma_f32_16x16x32_bf16 v[88:91], v[166:169], v[210:213], v[88:91]
	v_mfma_f32_16x16x32_bf16 v[76:79], v[144:147], v[218:221], v[76:79]
	v_mfma_f32_16x16x32_bf16 v[72:75], v[166:169], v[218:221], v[72:75]
	v_mfma_f32_16x16x32_bf16 v[124:127], v[162:165], v[198:201], v[124:127]
	v_mfma_f32_16x16x32_bf16 v[120:123], v[170:173], v[198:201], v[120:123]
	v_mfma_f32_16x16x32_bf16 v[108:111], v[162:165], v[206:209], v[108:111]
	v_mfma_f32_16x16x32_bf16 v[104:107], v[170:173], v[206:209], v[104:107]
	v_mfma_f32_16x16x32_bf16 v[92:95], v[162:165], v[214:217], v[92:95]
	v_mfma_f32_16x16x32_bf16 v[88:91], v[170:173], v[214:217], v[88:91]
	v_mfma_f32_16x16x32_bf16 v[76:79], v[162:165], v[222:225], v[76:79]
	v_mfma_f32_16x16x32_bf16 v[72:75], v[170:173], v[222:225], v[72:75]
	s_setprio 0
	s_setprio 1
	v_mfma_f32_16x16x32_bf16 v[116:119], v[174:177], v[190:193], v[116:119]
	v_mfma_f32_16x16x32_bf16 v[112:115], v[182:185], v[190:193], v[112:115]
	v_mfma_f32_16x16x32_bf16 v[100:103], v[174:177], v[202:205], v[100:103]
	v_mfma_f32_16x16x32_bf16 v[96:99], v[182:185], v[202:205], v[96:99]
	v_mfma_f32_16x16x32_bf16 v[84:87], v[174:177], v[210:213], v[84:87]
	v_mfma_f32_16x16x32_bf16 v[80:83], v[182:185], v[210:213], v[80:83]
	v_mfma_f32_16x16x32_bf16 v[68:71], v[174:177], v[218:221], v[68:71]
	v_mfma_f32_16x16x32_bf16 v[64:67], v[182:185], v[218:221], v[64:67]
	v_mfma_f32_16x16x32_bf16 v[116:119], v[178:181], v[198:201], v[116:119]
	v_mfma_f32_16x16x32_bf16 v[112:115], v[186:189], v[198:201], v[112:115]
	v_mfma_f32_16x16x32_bf16 v[100:103], v[178:181], v[206:209], v[100:103]
	v_mfma_f32_16x16x32_bf16 v[96:99], v[186:189], v[206:209], v[96:99]
	v_mfma_f32_16x16x32_bf16 v[84:87], v[178:181], v[214:217], v[84:87]
	v_mfma_f32_16x16x32_bf16 v[80:83], v[186:189], v[214:217], v[80:83]
	v_mfma_f32_16x16x32_bf16 v[68:71], v[178:181], v[222:225], v[68:71]
	v_mfma_f32_16x16x32_bf16 v[64:67], v[186:189], v[222:225], v[64:67]
	s_setprio 0
	s_barrier
	s_add_i32 s38, s66, s3
	v_lshl_add_u64 v[156:157], v[156:157], 0, s[12:13]
	s_mov_b32 m0, s38
	ds_read_b128 v[190:193], v155 offset:49152
	ds_read_b128 v[198:201], v155 offset:50176
	ds_read_b128 v[202:205], v155 offset:51200
	ds_read_b128 v[206:209], v155 offset:52224
	ds_read_b128 v[210:213], v155 offset:53248
	ds_read_b128 v[214:217], v155 offset:54272
	ds_read_b128 v[218:221], v155 offset:55296
	ds_read_b128 v[222:225], v155 offset:56320
	global_load_lds_dwordx4 v[156:157], off
	s_add_i32 m0, s38, 0x2000
	s_add_u32 s8, s8, 0x100080
	v_lshl_add_u64 v[156:157], v[226:227], 0, s[12:13]
	s_addc_u32 s9, s9, 0
	s_add_i32 s38, s67, s3
	global_load_lds_dwordx4 v[156:157], off
	v_lshl_add_u64 v[156:157], s[8:9], 0, v[130:131]
	s_mov_b32 m0, s38
	s_nop 0
	global_load_lds_dwordx4 v[156:157], off
	v_lshl_add_u64 v[156:157], s[8:9], 0, v[134:135]
	s_add_i32 m0, s38, 0x2000
	s_nop 0
	global_load_lds_dwordx4 v[156:157], off
	v_lshl_add_u64 v[156:157], v[228:229], 0, s[12:13]
	s_mov_b32 m0, s40
	s_nop 0
	global_load_lds_dwordx4 v[156:157], off
	v_lshl_add_u64 v[156:157], v[230:231], 0, s[12:13]
	s_mov_b32 m0, s41
	s_nop 0
	global_load_lds_dwordx4 v[156:157], off
	s_waitcnt vmcnt(8)
	s_waitcnt lgkmcnt(0)
	s_barrier
	s_setprio 1
	s_waitcnt lgkmcnt(0)
	v_mfma_f32_16x16x32_bf16 v[60:63], v[144:147], v[190:193], v[60:63]
	s_add_i32 s65, s65, 2
	v_mfma_f32_16x16x32_bf16 v[56:59], v[166:169], v[190:193], v[56:59]
	s_add_u32 s36, s36, 0x100
	v_mfma_f32_16x16x32_bf16 v[44:47], v[144:147], v[202:205], v[44:47]
	s_addc_u32 s37, s37, 0
	v_mfma_f32_16x16x32_bf16 v[40:43], v[166:169], v[202:205], v[40:43]
	s_add_u32 s61, s61, 0x100
	v_mfma_f32_16x16x32_bf16 v[28:31], v[144:147], v[210:213], v[28:31]
	s_addc_u32 s64, s64, 0
	v_mfma_f32_16x16x32_bf16 v[24:27], v[166:169], v[210:213], v[24:27]
	s_cmp_gt_u32 s65, 61
	v_mfma_f32_16x16x32_bf16 v[12:15], v[144:147], v[218:221], v[12:15]
	v_mfma_f32_16x16x32_bf16 v[8:11], v[166:169], v[218:221], v[8:11]
	v_mfma_f32_16x16x32_bf16 v[60:63], v[162:165], v[198:201], v[60:63]
	v_mfma_f32_16x16x32_bf16 v[56:59], v[170:173], v[198:201], v[56:59]
	v_mfma_f32_16x16x32_bf16 v[44:47], v[162:165], v[206:209], v[44:47]
	v_mfma_f32_16x16x32_bf16 v[40:43], v[170:173], v[206:209], v[40:43]
	v_mfma_f32_16x16x32_bf16 v[28:31], v[162:165], v[214:217], v[28:31]
	v_mfma_f32_16x16x32_bf16 v[24:27], v[170:173], v[214:217], v[24:27]
	v_mfma_f32_16x16x32_bf16 v[12:15], v[162:165], v[222:225], v[12:15]
	v_mfma_f32_16x16x32_bf16 v[8:11], v[170:173], v[222:225], v[8:11]
	s_setprio 0
	s_setprio 1
	v_mfma_f32_16x16x32_bf16 v[52:55], v[174:177], v[190:193], v[52:55]
	v_mfma_f32_16x16x32_bf16 v[48:51], v[182:185], v[190:193], v[48:51]
	v_mfma_f32_16x16x32_bf16 v[36:39], v[174:177], v[202:205], v[36:39]
	v_mfma_f32_16x16x32_bf16 v[32:35], v[182:185], v[202:205], v[32:35]
	v_mfma_f32_16x16x32_bf16 v[20:23], v[174:177], v[210:213], v[20:23]
	v_mfma_f32_16x16x32_bf16 v[16:19], v[182:185], v[210:213], v[16:19]
	v_mfma_f32_16x16x32_bf16 v[4:7], v[174:177], v[218:221], v[4:7]
	v_mfma_f32_16x16x32_bf16 v[0:3], v[182:185], v[218:221], v[0:3]
	v_mfma_f32_16x16x32_bf16 v[52:55], v[178:181], v[198:201], v[52:55]
	v_mfma_f32_16x16x32_bf16 v[48:51], v[186:189], v[198:201], v[48:51]
	v_mfma_f32_16x16x32_bf16 v[36:39], v[178:181], v[206:209], v[36:39]
	v_mfma_f32_16x16x32_bf16 v[32:35], v[186:189], v[206:209], v[32:35]
	v_mfma_f32_16x16x32_bf16 v[20:23], v[178:181], v[214:217], v[20:23]
	v_mfma_f32_16x16x32_bf16 v[16:19], v[186:189], v[214:217], v[16:19]
	v_mfma_f32_16x16x32_bf16 v[4:7], v[178:181], v[222:225], v[4:7]
	v_mfma_f32_16x16x32_bf16 v[0:3], v[186:189], v[222:225], v[0:3]
	s_setprio 0
	s_barrier
	s_cbranch_scc0 .LBB0_841
	s_and_b64 vcc, exec, s[14:15]
	s_cbranch_vccz .LBB0_844
	s_barrier

.LBB0_938:
	ds_read_b128 v[146:149], v169
	ds_read_b128 v[150:153], v169 offset:1024
	ds_read_b128 v[154:157], v169 offset:2048
	ds_read_b128 v[174:177], v169 offset:3072
	ds_read_b128 v[178:181], v170
	ds_read_b128 v[182:185], v170 offset:1024
	ds_read_b128 v[186:189], v170 offset:2048
	ds_read_b128 v[190:193], v170 offset:3072
	s_add_u32 s8, s26, 0xfffc0080
	s_addc_u32 s9, s27, -1
	s_cmp_eq_u32 s61, 12
	s_cselect_b32 s29, s15, s9
	s_cselect_b32 s28, s55, s8
	s_cselect_b32 s9, s13, s60
	s_cselect_b32 s8, s58, s59
	v_lshl_add_u64 v[230:231], s[26:27], 0, v[138:139]
	s_add_i32 m0, s5, 0xc000
	ds_read_b128 v[198:201], v171
	ds_read_b128 v[202:205], v171 offset:1024
	ds_read_b128 v[206:209], v171 offset:2048
	ds_read_b128 v[210:213], v171 offset:3072
	ds_read_b128 v[214:217], v171 offset:4096
	ds_read_b128 v[218:221], v171 offset:5120
	ds_read_b128 v[222:225], v171 offset:6144
	ds_read_b128 v[226:229], v171 offset:7168
	global_load_lds_dwordx4 v[230:231], off
	v_lshl_add_u64 v[230:231], s[26:27], 0, v[140:141]
	s_add_i32 m0, s5, 0xe000
	s_nop 0
	global_load_lds_dwordx4 v[230:231], off
	s_waitcnt vmcnt(8)
	s_waitcnt lgkmcnt(0)
	s_barrier
	s_setprio 1
	s_waitcnt lgkmcnt(0)
	v_mfma_f32_16x16x32_bf16 v[124:127], v[146:149], v[198:201], v[124:127]
	v_mfma_f32_16x16x32_bf16 v[120:123], v[154:157], v[198:201], v[120:123]
	v_mfma_f32_16x16x32_bf16 v[116:119], v[146:149], v[206:209], v[116:119]
	v_mfma_f32_16x16x32_bf16 v[108:111], v[154:157], v[206:209], v[108:111]
	v_mfma_f32_16x16x32_bf16 v[100:103], v[146:149], v[214:217], v[100:103]
	v_mfma_f32_16x16x32_bf16 v[92:95], v[154:157], v[214:217], v[92:95]
	v_mfma_f32_16x16x32_bf16 v[84:87], v[146:149], v[222:225], v[84:87]
	v_mfma_f32_16x16x32_bf16 v[76:79], v[154:157], v[222:225], v[76:79]
	v_mfma_f32_16x16x32_bf16 v[124:127], v[150:153], v[202:205], v[124:127]
	v_mfma_f32_16x16x32_bf16 v[120:123], v[174:177], v[202:205], v[120:123]
	v_mfma_f32_16x16x32_bf16 v[116:119], v[150:153], v[210:213], v[116:119]
	v_mfma_f32_16x16x32_bf16 v[108:111], v[174:177], v[210:213], v[108:111]
	v_mfma_f32_16x16x32_bf16 v[100:103], v[150:153], v[218:221], v[100:103]
	v_mfma_f32_16x16x32_bf16 v[92:95], v[174:177], v[218:221], v[92:95]
	v_mfma_f32_16x16x32_bf16 v[84:87], v[150:153], v[226:229], v[84:87]
	v_mfma_f32_16x16x32_bf16 v[76:79], v[174:177], v[226:229], v[76:79]
	s_setprio 0
	s_setprio 1
	v_mfma_f32_16x16x32_bf16 v[112:115], v[178:181], v[198:201], v[112:115]
	v_mfma_f32_16x16x32_bf16 v[104:107], v[186:189], v[198:201], v[104:107]
	v_mfma_f32_16x16x32_bf16 v[96:99], v[178:181], v[206:209], v[96:99]
	v_mfma_f32_16x16x32_bf16 v[88:91], v[186:189], v[206:209], v[88:91]
	v_mfma_f32_16x16x32_bf16 v[80:83], v[178:181], v[214:217], v[80:83]
	v_mfma_f32_16x16x32_bf16 v[72:75], v[186:189], v[214:217], v[72:75]
	v_mfma_f32_16x16x32_bf16 v[68:71], v[178:181], v[222:225], v[68:71]
	v_mfma_f32_16x16x32_bf16 v[64:67], v[186:189], v[222:225], v[64:67]
	v_mfma_f32_16x16x32_bf16 v[112:115], v[182:185], v[202:205], v[112:115]
	v_mfma_f32_16x16x32_bf16 v[104:107], v[190:193], v[202:205], v[104:107]
	v_mfma_f32_16x16x32_bf16 v[96:99], v[182:185], v[210:213], v[96:99]
	v_mfma_f32_16x16x32_bf16 v[88:91], v[190:193], v[210:213], v[88:91]
	v_mfma_f32_16x16x32_bf16 v[80:83], v[182:185], v[218:221], v[80:83]
	v_mfma_f32_16x16x32_bf16 v[72:75], v[190:193], v[218:221], v[72:75]
	v_mfma_f32_16x16x32_bf16 v[68:71], v[182:185], v[226:229], v[68:71]
	v_mfma_f32_16x16x32_bf16 v[64:67], v[190:193], v[226:229], v[64:67]
	s_setprio 0
	s_barrier
	s_add_i32 s62, s37, s3
	v_lshl_add_u64 v[230:231], s[8:9], 0, v[132:133]
	s_mov_b32 m0, s62
	ds_read_b128 v[198:201], v171 offset:16384
	ds_read_b128 v[202:205], v171 offset:17408
	ds_read_b128 v[206:209], v171 offset:18432
	ds_read_b128 v[210:213], v171 offset:19456
	ds_read_b128 v[214:217], v171 offset:20480
	ds_read_b128 v[218:221], v171 offset:21504
	ds_read_b128 v[222:225], v171 offset:22528
	ds_read_b128 v[226:229], v171 offset:23552
	global_load_lds_dwordx4 v[230:231], off
	s_add_i32 m0, s62, 0x2000
	s_add_u32 s62, s8, 0x40000
	v_lshl_add_u64 v[232:233], s[8:9], 0, v[128:129]
	s_addc_u32 s63, s9, 0
	s_add_i32 s64, s38, s3
	global_load_lds_dwordx4 v[232:233], off
	v_lshl_add_u64 v[234:235], s[62:63], 0, v[132:133]
	s_mov_b32 m0, s64
	v_lshl_add_u64 v[236:237], s[28:29], 0, v[130:131]
	global_load_lds_dwordx4 v[234:235], off
	v_lshl_add_u64 v[234:235], s[62:63], 0, v[128:129]
	s_add_i32 m0, s64, 0x2000
	s_nop 0
	global_load_lds_dwordx4 v[234:235], off
	v_lshl_add_u64 v[234:235], s[28:29], 0, v[134:135]
	s_mov_b32 m0, s5
	s_nop 0
	global_load_lds_dwordx4 v[234:235], off
	s_mov_b32 m0, s25
	s_nop 0
	global_load_lds_dwordx4 v[236:237], off
	s_waitcnt vmcnt(8)
	s_waitcnt lgkmcnt(0)
	s_barrier
	s_setprio 1
	s_waitcnt lgkmcnt(0)
	v_mfma_f32_16x16x32_bf16 v[60:63], v[146:149], v[198:201], v[60:63]
	v_mfma_f32_16x16x32_bf16 v[56:59], v[154:157], v[198:201], v[56:59]
	v_mfma_f32_16x16x32_bf16 v[52:55], v[146:149], v[206:209], v[52:55]
	v_mfma_f32_16x16x32_bf16 v[44:47], v[154:157], v[206:209], v[44:47]
	v_mfma_f32_16x16x32_bf16 v[32:35], v[146:149], v[214:217], v[32:35]
	v_mfma_f32_16x16x32_bf16 v[24:27], v[154:157], v[214:217], v[24:27]
	v_mfma_f32_16x16x32_bf16 v[20:23], v[146:149], v[222:225], v[20:23]
	v_mfma_f32_16x16x32_bf16 v[12:15], v[154:157], v[222:225], v[12:15]
	v_mfma_f32_16x16x32_bf16 v[60:63], v[150:153], v[202:205], v[60:63]
	v_mfma_f32_16x16x32_bf16 v[56:59], v[174:177], v[202:205], v[56:59]
	v_mfma_f32_16x16x32_bf16 v[52:55], v[150:153], v[210:213], v[52:55]
	v_mfma_f32_16x16x32_bf16 v[44:47], v[174:177], v[210:213], v[44:47]
	v_mfma_f32_16x16x32_bf16 v[32:35], v[150:153], v[218:221], v[32:35]
	v_mfma_f32_16x16x32_bf16 v[24:27], v[174:177], v[218:221], v[24:27]
	v_mfma_f32_16x16x32_bf16 v[20:23], v[150:153], v[226:229], v[20:23]
	v_mfma_f32_16x16x32_bf16 v[12:15], v[174:177], v[226:229], v[12:15]
	s_setprio 0
	s_setprio 1
	v_mfma_f32_16x16x32_bf16 v[48:51], v[178:181], v[198:201], v[48:51]
	v_mfma_f32_16x16x32_bf16 v[40:43], v[186:189], v[198:201], v[40:43]
	v_mfma_f32_16x16x32_bf16 v[36:39], v[178:181], v[206:209], v[36:39]
	v_mfma_f32_16x16x32_bf16 v[28:31], v[186:189], v[206:209], v[28:31]
	v_mfma_f32_16x16x32_bf16 v[16:19], v[178:181], v[214:217], v[16:19]
	v_mfma_f32_16x16x32_bf16 v[8:11], v[186:189], v[214:217], v[8:11]
	v_mfma_f32_16x16x32_bf16 v[4:7], v[178:181], v[222:225], v[4:7]
	v_mfma_f32_16x16x32_bf16 v[0:3], v[186:189], v[222:225], v[0:3]
	v_mfma_f32_16x16x32_bf16 v[48:51], v[182:185], v[202:205], v[48:51]
	v_mfma_f32_16x16x32_bf16 v[40:43], v[190:193], v[202:205], v[40:43]
	v_mfma_f32_16x16x32_bf16 v[36:39], v[182:185], v[210:213], v[36:39]
	v_mfma_f32_16x16x32_bf16 v[28:31], v[190:193], v[210:213], v[28:31]
	v_mfma_f32_16x16x32_bf16 v[16:19], v[182:185], v[218:221], v[16:19]
	v_mfma_f32_16x16x32_bf16 v[8:11], v[190:193], v[218:221], v[8:11]
	v_mfma_f32_16x16x32_bf16 v[4:7], v[182:185], v[226:229], v[4:7]
	v_mfma_f32_16x16x32_bf16 v[0:3], v[190:193], v[226:229], v[0:3]
	s_setprio 0
	s_barrier
	s_add_i32 s62, 0, 0x18000
	s_add_i32 s63, 0, 0x1c000
	v_add_u32_e32 v174, s62, v162
	v_add_u32_e32 v190, s63, v162
	ds_read_b128 v[146:149], v174
	ds_read_b128 v[150:153], v174 offset:1024
	ds_read_b128 v[154:157], v174 offset:2048
	ds_read_b128 v[174:177], v174 offset:3072
	ds_read_b128 v[178:181], v190
	ds_read_b128 v[182:185], v190 offset:1024
	ds_read_b128 v[186:189], v190 offset:2048
	ds_read_b128 v[190:193], v190 offset:3072
	s_add_u32 s28, s28, 0x40000
	s_addc_u32 s29, s29, 0
	s_mov_b32 m0, s30
	v_lshl_add_u64 v[238:239], s[28:29], 0, v[134:135]
	ds_read_b128 v[198:201], v171 offset:32768
	ds_read_b128 v[202:205], v171 offset:33792
	ds_read_b128 v[206:209], v171 offset:34816
	ds_read_b128 v[210:213], v171 offset:35840
	ds_read_b128 v[214:217], v171 offset:36864
	ds_read_b128 v[218:221], v171 offset:37888
	ds_read_b128 v[222:225], v171 offset:38912
	ds_read_b128 v[226:229], v171 offset:39936
	global_load_lds_dwordx4 v[238:239], off
	v_lshl_add_u64 v[238:239], s[28:29], 0, v[130:131]
	s_mov_b32 m0, s31
	s_nop 0
	global_load_lds_dwordx4 v[238:239], off
	s_waitcnt vmcnt(8)
	s_waitcnt lgkmcnt(0)
	s_barrier
	s_setprio 1
	s_waitcnt lgkmcnt(0)
	v_mfma_f32_16x16x32_bf16 v[124:127], v[146:149], v[198:201], v[124:127]
	v_mfma_f32_16x16x32_bf16 v[120:123], v[154:157], v[198:201], v[120:123]
	v_mfma_f32_16x16x32_bf16 v[116:119], v[146:149], v[206:209], v[116:119]
	v_mfma_f32_16x16x32_bf16 v[108:111], v[154:157], v[206:209], v[108:111]
	v_mfma_f32_16x16x32_bf16 v[100:103], v[146:149], v[214:217], v[100:103]
	v_mfma_f32_16x16x32_bf16 v[92:95], v[154:157], v[214:217], v[92:95]
	v_mfma_f32_16x16x32_bf16 v[84:87], v[146:149], v[222:225], v[84:87]
	v_mfma_f32_16x16x32_bf16 v[76:79], v[154:157], v[222:225], v[76:79]
	v_mfma_f32_16x16x32_bf16 v[124:127], v[150:153], v[202:205], v[124:127]
	v_mfma_f32_16x16x32_bf16 v[120:123], v[174:177], v[202:205], v[120:123]
	v_mfma_f32_16x16x32_bf16 v[116:119], v[150:153], v[210:213], v[116:119]
	v_mfma_f32_16x16x32_bf16 v[108:111], v[174:177], v[210:213], v[108:111]
	v_mfma_f32_16x16x32_bf16 v[100:103], v[150:153], v[218:221], v[100:103]
	v_mfma_f32_16x16x32_bf16 v[92:95], v[174:177], v[218:221], v[92:95]
	v_mfma_f32_16x16x32_bf16 v[84:87], v[150:153], v[226:229], v[84:87]
	v_mfma_f32_16x16x32_bf16 v[76:79], v[174:177], v[226:229], v[76:79]
	s_setprio 0
	s_setprio 1
	v_mfma_f32_16x16x32_bf16 v[112:115], v[178:181], v[198:201], v[112:115]
	v_mfma_f32_16x16x32_bf16 v[104:107], v[186:189], v[198:201], v[104:107]
	v_mfma_f32_16x16x32_bf16 v[96:99], v[178:181], v[206:209], v[96:99]
	v_mfma_f32_16x16x32_bf16 v[88:91], v[186:189], v[206:209], v[88:91]
	v_mfma_f32_16x16x32_bf16 v[80:83], v[178:181], v[214:217], v[80:83]
	v_mfma_f32_16x16x32_bf16 v[72:75], v[186:189], v[214:217], v[72:75]
	v_mfma_f32_16x16x32_bf16 v[68:71], v[178:181], v[222:225], v[68:71]
	v_mfma_f32_16x16x32_bf16 v[64:67], v[186:189], v[222:225], v[64:67]
	v_mfma_f32_16x16x32_bf16 v[112:115], v[182:185], v[202:205], v[112:115]
	v_mfma_f32_16x16x32_bf16 v[104:107], v[190:193], v[202:205], v[104:107]
	v_mfma_f32_16x16x32_bf16 v[96:99], v[182:185], v[210:213], v[96:99]
	v_mfma_f32_16x16x32_bf16 v[88:91], v[190:193], v[210:213], v[88:91]
	v_mfma_f32_16x16x32_bf16 v[80:83], v[182:185], v[218:221], v[80:83]
	v_mfma_f32_16x16x32_bf16 v[72:75], v[190:193], v[218:221], v[72:75]
	v_mfma_f32_16x16x32_bf16 v[68:71], v[182:185], v[226:229], v[68:71]
	v_mfma_f32_16x16x32_bf16 v[64:67], v[190:193], v[226:229], v[64:67]
	s_setprio 0
	s_barrier
	s_add_i32 s28, s62, s3
	v_lshl_add_u64 v[230:231], v[230:231], 0, s[6:7]
	s_mov_b32 m0, s28
	ds_read_b128 v[198:201], v171 offset:49152
	ds_read_b128 v[202:205], v171 offset:50176
	ds_read_b128 v[206:209], v171 offset:51200
	ds_read_b128 v[210:213], v171 offset:52224
	ds_read_b128 v[214:217], v171 offset:53248
	ds_read_b128 v[218:221], v171 offset:54272
	ds_read_b128 v[222:225], v171 offset:55296
	ds_read_b128 v[226:229], v171 offset:56320
	global_load_lds_dwordx4 v[230:231], off
	s_add_i32 m0, s28, 0x2000
	s_add_u32 s8, s8, 0x40080
	v_lshl_add_u64 v[230:231], v[232:233], 0, s[6:7]
	s_addc_u32 s9, s9, 0
	s_add_i32 s28, s63, s3
	global_load_lds_dwordx4 v[230:231], off
	v_lshl_add_u64 v[230:231], s[8:9], 0, v[132:133]
	s_mov_b32 m0, s28
	s_nop 0
	global_load_lds_dwordx4 v[230:231], off
	v_lshl_add_u64 v[230:231], s[8:9], 0, v[128:129]
	s_add_i32 m0, s28, 0x2000
	s_nop 0
	global_load_lds_dwordx4 v[230:231], off
	v_lshl_add_u64 v[230:231], v[234:235], 0, s[6:7]
	s_mov_b32 m0, s33
	s_nop 0
	global_load_lds_dwordx4 v[230:231], off
	v_lshl_add_u64 v[230:231], v[236:237], 0, s[6:7]
	s_mov_b32 m0, s36
	s_nop 0
	global_load_lds_dwordx4 v[230:231], off
	s_waitcnt vmcnt(8)
	s_waitcnt lgkmcnt(0)
	s_barrier
	s_setprio 1
	s_waitcnt lgkmcnt(0)
	v_mfma_f32_16x16x32_bf16 v[60:63], v[146:149], v[198:201], v[60:63]
	s_add_i32 s61, s61, 2
	v_mfma_f32_16x16x32_bf16 v[56:59], v[154:157], v[198:201], v[56:59]
	s_add_u32 s26, s26, 0x100
	v_mfma_f32_16x16x32_bf16 v[52:55], v[146:149], v[206:209], v[52:55]
	s_addc_u32 s27, s27, 0
	v_mfma_f32_16x16x32_bf16 v[44:47], v[154:157], v[206:209], v[44:47]
	s_add_u32 s59, s59, 0x100
	v_mfma_f32_16x16x32_bf16 v[32:35], v[146:149], v[214:217], v[32:35]
	s_addc_u32 s60, s60, 0
	v_mfma_f32_16x16x32_bf16 v[24:27], v[154:157], v[214:217], v[24:27]
	s_cmp_gt_u32 s61, 13
	v_mfma_f32_16x16x32_bf16 v[20:23], v[146:149], v[222:225], v[20:23]
	v_mfma_f32_16x16x32_bf16 v[12:15], v[154:157], v[222:225], v[12:15]
	v_mfma_f32_16x16x32_bf16 v[60:63], v[150:153], v[202:205], v[60:63]
	v_mfma_f32_16x16x32_bf16 v[56:59], v[174:177], v[202:205], v[56:59]
	v_mfma_f32_16x16x32_bf16 v[52:55], v[150:153], v[210:213], v[52:55]
	v_mfma_f32_16x16x32_bf16 v[44:47], v[174:177], v[210:213], v[44:47]
	v_mfma_f32_16x16x32_bf16 v[32:35], v[150:153], v[218:221], v[32:35]
	v_mfma_f32_16x16x32_bf16 v[24:27], v[174:177], v[218:221], v[24:27]
	v_mfma_f32_16x16x32_bf16 v[20:23], v[150:153], v[226:229], v[20:23]
	v_mfma_f32_16x16x32_bf16 v[12:15], v[174:177], v[226:229], v[12:15]
	s_setprio 0
	s_setprio 1
	v_mfma_f32_16x16x32_bf16 v[48:51], v[178:181], v[198:201], v[48:51]
	v_mfma_f32_16x16x32_bf16 v[40:43], v[186:189], v[198:201], v[40:43]
	v_mfma_f32_16x16x32_bf16 v[36:39], v[178:181], v[206:209], v[36:39]
	v_mfma_f32_16x16x32_bf16 v[28:31], v[186:189], v[206:209], v[28:31]
	v_mfma_f32_16x16x32_bf16 v[16:19], v[178:181], v[214:217], v[16:19]
	v_mfma_f32_16x16x32_bf16 v[8:11], v[186:189], v[214:217], v[8:11]
	v_mfma_f32_16x16x32_bf16 v[4:7], v[178:181], v[222:225], v[4:7]
	v_mfma_f32_16x16x32_bf16 v[0:3], v[186:189], v[222:225], v[0:3]
	v_mfma_f32_16x16x32_bf16 v[48:51], v[182:185], v[202:205], v[48:51]
	v_mfma_f32_16x16x32_bf16 v[40:43], v[190:193], v[202:205], v[40:43]
	v_mfma_f32_16x16x32_bf16 v[36:39], v[182:185], v[210:213], v[36:39]
	v_mfma_f32_16x16x32_bf16 v[28:31], v[190:193], v[210:213], v[28:31]
	v_mfma_f32_16x16x32_bf16 v[16:19], v[182:185], v[218:221], v[16:19]
	v_mfma_f32_16x16x32_bf16 v[8:11], v[190:193], v[218:221], v[8:11]
	v_mfma_f32_16x16x32_bf16 v[4:7], v[182:185], v[226:229], v[4:7]
	v_mfma_f32_16x16x32_bf16 v[0:3], v[190:193], v[226:229], v[0:3]
	s_setprio 0
	s_barrier
	s_cbranch_scc0 .LBB0_938
	s_and_b64 vcc, exec, s[10:11]
	s_cbranch_vccz .LBB0_941
	s_barrier

.LBB0_1226:
	ds_read_b128 v[144:147], v151
	ds_read_b128 v[154:157], v151 offset:1024
	ds_read_b128 v[158:161], v151 offset:2048
	ds_read_b128 v[162:165], v151 offset:3072
	ds_read_b128 v[166:169], v152
	ds_read_b128 v[170:173], v152 offset:1024
	ds_read_b128 v[174:177], v152 offset:2048
	ds_read_b128 v[178:181], v152 offset:3072
	s_add_u32 s8, s28, 0xfffc0080
	s_addc_u32 s9, s29, -1
	s_cmp_eq_u32 s58, 12
	s_cselect_b32 s31, s21, s9
	s_cselect_b32 s30, s27, s8
	s_cselect_b32 s9, s17, s57
	s_cselect_b32 s8, s53, s55
	v_lshl_add_u64 v[196:197], s[28:29], 0, v[136:137]
	s_add_i32 m0, s4, 0xc000
	ds_read_b128 v[182:185], v153
	ds_read_b128 v[186:189], v153 offset:1024
	ds_read_b128 v[190:193], v153 offset:2048
	ds_read_b128 v[200:203], v153 offset:3072
	ds_read_b128 v[204:207], v153 offset:4096
	ds_read_b128 v[208:211], v153 offset:5120
	ds_read_b128 v[212:215], v153 offset:6144
	ds_read_b128 v[216:219], v153 offset:7168
	global_load_lds_dwordx4 v[196:197], off
	v_lshl_add_u64 v[196:197], s[28:29], 0, v[138:139]
	s_add_i32 m0, s4, 0xe000
	s_nop 0
	global_load_lds_dwordx4 v[196:197], off
	s_waitcnt vmcnt(8)
	s_waitcnt lgkmcnt(0)
	s_barrier
	s_setprio 1
	s_waitcnt lgkmcnt(0)
	v_mfma_f32_16x16x32_bf16 v[124:127], v[144:147], v[182:185], v[124:127]
	v_mfma_f32_16x16x32_bf16 v[120:123], v[158:161], v[182:185], v[120:123]
	v_mfma_f32_16x16x32_bf16 v[108:111], v[144:147], v[190:193], v[108:111]
	v_mfma_f32_16x16x32_bf16 v[104:107], v[158:161], v[190:193], v[104:107]
	v_mfma_f32_16x16x32_bf16 v[92:95], v[144:147], v[204:207], v[92:95]
	v_mfma_f32_16x16x32_bf16 v[88:91], v[158:161], v[204:207], v[88:91]
	v_mfma_f32_16x16x32_bf16 v[76:79], v[144:147], v[212:215], v[76:79]
	v_mfma_f32_16x16x32_bf16 v[72:75], v[158:161], v[212:215], v[72:75]
	v_mfma_f32_16x16x32_bf16 v[124:127], v[154:157], v[186:189], v[124:127]
	v_mfma_f32_16x16x32_bf16 v[120:123], v[162:165], v[186:189], v[120:123]
	v_mfma_f32_16x16x32_bf16 v[108:111], v[154:157], v[200:203], v[108:111]
	v_mfma_f32_16x16x32_bf16 v[104:107], v[162:165], v[200:203], v[104:107]
	v_mfma_f32_16x16x32_bf16 v[92:95], v[154:157], v[208:211], v[92:95]
	v_mfma_f32_16x16x32_bf16 v[88:91], v[162:165], v[208:211], v[88:91]
	v_mfma_f32_16x16x32_bf16 v[76:79], v[154:157], v[216:219], v[76:79]
	v_mfma_f32_16x16x32_bf16 v[72:75], v[162:165], v[216:219], v[72:75]
	s_setprio 0
	s_setprio 1
	v_mfma_f32_16x16x32_bf16 v[116:119], v[166:169], v[182:185], v[116:119]
	v_mfma_f32_16x16x32_bf16 v[112:115], v[174:177], v[182:185], v[112:115]
	v_mfma_f32_16x16x32_bf16 v[100:103], v[166:169], v[190:193], v[100:103]
	v_mfma_f32_16x16x32_bf16 v[96:99], v[174:177], v[190:193], v[96:99]
	v_mfma_f32_16x16x32_bf16 v[84:87], v[166:169], v[204:207], v[84:87]
	v_mfma_f32_16x16x32_bf16 v[80:83], v[174:177], v[204:207], v[80:83]
	v_mfma_f32_16x16x32_bf16 v[68:71], v[166:169], v[212:215], v[68:71]
	v_mfma_f32_16x16x32_bf16 v[64:67], v[174:177], v[212:215], v[64:67]
	v_mfma_f32_16x16x32_bf16 v[116:119], v[170:173], v[186:189], v[116:119]
	v_mfma_f32_16x16x32_bf16 v[112:115], v[178:181], v[186:189], v[112:115]
	v_mfma_f32_16x16x32_bf16 v[100:103], v[170:173], v[200:203], v[100:103]
	v_mfma_f32_16x16x32_bf16 v[96:99], v[178:181], v[200:203], v[96:99]
	v_mfma_f32_16x16x32_bf16 v[84:87], v[170:173], v[208:211], v[84:87]
	v_mfma_f32_16x16x32_bf16 v[80:83], v[178:181], v[208:211], v[80:83]
	v_mfma_f32_16x16x32_bf16 v[68:71], v[170:173], v[216:219], v[68:71]
	v_mfma_f32_16x16x32_bf16 v[64:67], v[178:181], v[216:219], v[64:67]
	s_setprio 0
	s_barrier
	s_add_i32 s59, s40, s3
	v_lshl_add_u64 v[196:197], s[8:9], 0, v[130:131]
	s_mov_b32 m0, s59
	ds_read_b128 v[182:185], v153 offset:16384
	ds_read_b128 v[186:189], v153 offset:17408
	ds_read_b128 v[190:193], v153 offset:18432
	ds_read_b128 v[200:203], v153 offset:19456
	ds_read_b128 v[204:207], v153 offset:20480
	ds_read_b128 v[208:211], v153 offset:21504
	ds_read_b128 v[212:215], v153 offset:22528
	ds_read_b128 v[216:219], v153 offset:23552
	global_load_lds_dwordx4 v[196:197], off
	s_add_i32 m0, s59, 0x2000
	s_add_u32 s60, s8, 0x40000
	v_lshl_add_u64 v[220:221], s[8:9], 0, v[134:135]
	s_addc_u32 s61, s9, 0
	s_add_i32 s59, s41, s3
	global_load_lds_dwordx4 v[220:221], off
	v_lshl_add_u64 v[222:223], s[60:61], 0, v[130:131]
	s_mov_b32 m0, s59
	v_lshl_add_u64 v[224:225], s[30:31], 0, v[132:133]
	global_load_lds_dwordx4 v[222:223], off
	v_lshl_add_u64 v[222:223], s[60:61], 0, v[134:135]
	s_add_i32 m0, s59, 0x2000
	s_nop 0
	global_load_lds_dwordx4 v[222:223], off
	v_lshl_add_u64 v[222:223], s[30:31], 0, v[128:129]
	s_mov_b32 m0, s4
	s_nop 0
	global_load_lds_dwordx4 v[222:223], off
	s_mov_b32 m0, s5
	s_nop 0
	global_load_lds_dwordx4 v[224:225], off
	s_waitcnt vmcnt(8)
	s_waitcnt lgkmcnt(0)
	s_barrier
	s_setprio 1
	s_waitcnt lgkmcnt(0)
	v_mfma_f32_16x16x32_bf16 v[60:63], v[144:147], v[182:185], v[60:63]
	v_mfma_f32_16x16x32_bf16 v[56:59], v[158:161], v[182:185], v[56:59]
	v_mfma_f32_16x16x32_bf16 v[44:47], v[144:147], v[190:193], v[44:47]
	v_mfma_f32_16x16x32_bf16 v[40:43], v[158:161], v[190:193], v[40:43]
	v_mfma_f32_16x16x32_bf16 v[28:31], v[144:147], v[204:207], v[28:31]
	v_mfma_f32_16x16x32_bf16 v[24:27], v[158:161], v[204:207], v[24:27]
	v_mfma_f32_16x16x32_bf16 v[12:15], v[144:147], v[212:215], v[12:15]
	v_mfma_f32_16x16x32_bf16 v[8:11], v[158:161], v[212:215], v[8:11]
	v_mfma_f32_16x16x32_bf16 v[60:63], v[154:157], v[186:189], v[60:63]
	v_mfma_f32_16x16x32_bf16 v[56:59], v[162:165], v[186:189], v[56:59]
	v_mfma_f32_16x16x32_bf16 v[44:47], v[154:157], v[200:203], v[44:47]
	v_mfma_f32_16x16x32_bf16 v[40:43], v[162:165], v[200:203], v[40:43]
	v_mfma_f32_16x16x32_bf16 v[28:31], v[154:157], v[208:211], v[28:31]
	v_mfma_f32_16x16x32_bf16 v[24:27], v[162:165], v[208:211], v[24:27]
	v_mfma_f32_16x16x32_bf16 v[12:15], v[154:157], v[216:219], v[12:15]
	v_mfma_f32_16x16x32_bf16 v[8:11], v[162:165], v[216:219], v[8:11]
	s_setprio 0
	s_setprio 1
	v_mfma_f32_16x16x32_bf16 v[52:55], v[166:169], v[182:185], v[52:55]
	v_mfma_f32_16x16x32_bf16 v[48:51], v[174:177], v[182:185], v[48:51]
	v_mfma_f32_16x16x32_bf16 v[36:39], v[166:169], v[190:193], v[36:39]
	v_mfma_f32_16x16x32_bf16 v[32:35], v[174:177], v[190:193], v[32:35]
	v_mfma_f32_16x16x32_bf16 v[20:23], v[166:169], v[204:207], v[20:23]
	v_mfma_f32_16x16x32_bf16 v[16:19], v[174:177], v[204:207], v[16:19]
	v_mfma_f32_16x16x32_bf16 v[4:7], v[166:169], v[212:215], v[4:7]
	v_mfma_f32_16x16x32_bf16 v[0:3], v[174:177], v[212:215], v[0:3]
	v_mfma_f32_16x16x32_bf16 v[52:55], v[170:173], v[186:189], v[52:55]
	v_mfma_f32_16x16x32_bf16 v[48:51], v[178:181], v[186:189], v[48:51]
	v_mfma_f32_16x16x32_bf16 v[36:39], v[170:173], v[200:203], v[36:39]
	v_mfma_f32_16x16x32_bf16 v[32:35], v[178:181], v[200:203], v[32:35]
	v_mfma_f32_16x16x32_bf16 v[20:23], v[170:173], v[208:211], v[20:23]
	v_mfma_f32_16x16x32_bf16 v[16:19], v[178:181], v[208:211], v[16:19]
	v_mfma_f32_16x16x32_bf16 v[4:7], v[170:173], v[216:219], v[4:7]
	v_mfma_f32_16x16x32_bf16 v[0:3], v[178:181], v[216:219], v[0:3]
	s_setprio 0
	s_barrier
	s_add_i32 s59, 0, 0x18000
	s_add_i32 s60, 0, 0x1c000
	v_add_u32_e32 v162, s59, v149
	v_add_u32_e32 v178, s60, v149
	ds_read_b128 v[144:147], v162
	ds_read_b128 v[154:157], v162 offset:1024
	ds_read_b128 v[158:161], v162 offset:2048
	ds_read_b128 v[162:165], v162 offset:3072
	ds_read_b128 v[166:169], v178
	ds_read_b128 v[170:173], v178 offset:1024
	ds_read_b128 v[174:177], v178 offset:2048
	ds_read_b128 v[178:181], v178 offset:3072
	s_add_u32 s30, s30, 0x40000
	s_addc_u32 s31, s31, 0
	s_mov_b32 m0, s33
	v_lshl_add_u64 v[226:227], s[30:31], 0, v[128:129]
	ds_read_b128 v[182:185], v153 offset:32768
	ds_read_b128 v[186:189], v153 offset:33792
	ds_read_b128 v[190:193], v153 offset:34816
	ds_read_b128 v[200:203], v153 offset:35840
	ds_read_b128 v[204:207], v153 offset:36864
	ds_read_b128 v[208:211], v153 offset:37888
	ds_read_b128 v[212:215], v153 offset:38912
	ds_read_b128 v[216:219], v153 offset:39936
	global_load_lds_dwordx4 v[226:227], off
	v_lshl_add_u64 v[226:227], s[30:31], 0, v[132:133]
	s_mov_b32 m0, s36
	s_nop 0
	global_load_lds_dwordx4 v[226:227], off
	s_waitcnt vmcnt(8)
	s_waitcnt lgkmcnt(0)
	s_barrier
	s_setprio 1
	s_waitcnt lgkmcnt(0)
	v_mfma_f32_16x16x32_bf16 v[124:127], v[144:147], v[182:185], v[124:127]
	v_mfma_f32_16x16x32_bf16 v[120:123], v[158:161], v[182:185], v[120:123]
	v_mfma_f32_16x16x32_bf16 v[108:111], v[144:147], v[190:193], v[108:111]
	v_mfma_f32_16x16x32_bf16 v[104:107], v[158:161], v[190:193], v[104:107]
	v_mfma_f32_16x16x32_bf16 v[92:95], v[144:147], v[204:207], v[92:95]
	v_mfma_f32_16x16x32_bf16 v[88:91], v[158:161], v[204:207], v[88:91]
	v_mfma_f32_16x16x32_bf16 v[76:79], v[144:147], v[212:215], v[76:79]
	v_mfma_f32_16x16x32_bf16 v[72:75], v[158:161], v[212:215], v[72:75]
	v_mfma_f32_16x16x32_bf16 v[124:127], v[154:157], v[186:189], v[124:127]
	v_mfma_f32_16x16x32_bf16 v[120:123], v[162:165], v[186:189], v[120:123]
	v_mfma_f32_16x16x32_bf16 v[108:111], v[154:157], v[200:203], v[108:111]
	v_mfma_f32_16x16x32_bf16 v[104:107], v[162:165], v[200:203], v[104:107]
	v_mfma_f32_16x16x32_bf16 v[92:95], v[154:157], v[208:211], v[92:95]
	v_mfma_f32_16x16x32_bf16 v[88:91], v[162:165], v[208:211], v[88:91]
	v_mfma_f32_16x16x32_bf16 v[76:79], v[154:157], v[216:219], v[76:79]
	v_mfma_f32_16x16x32_bf16 v[72:75], v[162:165], v[216:219], v[72:75]
	s_setprio 0
	s_setprio 1
	v_mfma_f32_16x16x32_bf16 v[116:119], v[166:169], v[182:185], v[116:119]
	v_mfma_f32_16x16x32_bf16 v[112:115], v[174:177], v[182:185], v[112:115]
	v_mfma_f32_16x16x32_bf16 v[100:103], v[166:169], v[190:193], v[100:103]
	v_mfma_f32_16x16x32_bf16 v[96:99], v[174:177], v[190:193], v[96:99]
	v_mfma_f32_16x16x32_bf16 v[84:87], v[166:169], v[204:207], v[84:87]
	v_mfma_f32_16x16x32_bf16 v[80:83], v[174:177], v[204:207], v[80:83]
	v_mfma_f32_16x16x32_bf16 v[68:71], v[166:169], v[212:215], v[68:71]
	v_mfma_f32_16x16x32_bf16 v[64:67], v[174:177], v[212:215], v[64:67]
	v_mfma_f32_16x16x32_bf16 v[116:119], v[170:173], v[186:189], v[116:119]
	v_mfma_f32_16x16x32_bf16 v[112:115], v[178:181], v[186:189], v[112:115]
	v_mfma_f32_16x16x32_bf16 v[100:103], v[170:173], v[200:203], v[100:103]
	v_mfma_f32_16x16x32_bf16 v[96:99], v[178:181], v[200:203], v[96:99]
	v_mfma_f32_16x16x32_bf16 v[84:87], v[170:173], v[208:211], v[84:87]
	v_mfma_f32_16x16x32_bf16 v[80:83], v[178:181], v[208:211], v[80:83]
	v_mfma_f32_16x16x32_bf16 v[68:71], v[170:173], v[216:219], v[68:71]
	v_mfma_f32_16x16x32_bf16 v[64:67], v[178:181], v[216:219], v[64:67]
	s_setprio 0
	s_barrier
	s_add_i32 s30, s59, s3
	v_lshl_add_u64 v[196:197], v[196:197], 0, s[12:13]
	s_mov_b32 m0, s30
	ds_read_b128 v[182:185], v153 offset:49152
	ds_read_b128 v[186:189], v153 offset:50176
	ds_read_b128 v[190:193], v153 offset:51200
	ds_read_b128 v[200:203], v153 offset:52224
	ds_read_b128 v[204:207], v153 offset:53248
	ds_read_b128 v[208:211], v153 offset:54272
	ds_read_b128 v[212:215], v153 offset:55296
	ds_read_b128 v[216:219], v153 offset:56320
	global_load_lds_dwordx4 v[196:197], off
	s_add_i32 m0, s30, 0x2000
	s_add_u32 s8, s8, 0x40080
	v_lshl_add_u64 v[196:197], v[220:221], 0, s[12:13]
	s_addc_u32 s9, s9, 0
	s_add_i32 s30, s60, s3
	global_load_lds_dwordx4 v[196:197], off
	v_lshl_add_u64 v[196:197], s[8:9], 0, v[130:131]
	s_mov_b32 m0, s30
	s_nop 0
	global_load_lds_dwordx4 v[196:197], off
	v_lshl_add_u64 v[196:197], s[8:9], 0, v[134:135]
	s_add_i32 m0, s30, 0x2000
	s_nop 0
	global_load_lds_dwordx4 v[196:197], off
	v_lshl_add_u64 v[196:197], v[222:223], 0, s[12:13]
	s_mov_b32 m0, s38
	s_nop 0
	global_load_lds_dwordx4 v[196:197], off
	v_lshl_add_u64 v[196:197], v[224:225], 0, s[12:13]
	s_mov_b32 m0, s39
	s_nop 0
	global_load_lds_dwordx4 v[196:197], off
	s_waitcnt vmcnt(8)
	s_waitcnt lgkmcnt(0)
	s_barrier
	s_setprio 1
	s_waitcnt lgkmcnt(0)
	v_mfma_f32_16x16x32_bf16 v[60:63], v[144:147], v[182:185], v[60:63]
	s_add_i32 s58, s58, 2
	v_mfma_f32_16x16x32_bf16 v[56:59], v[158:161], v[182:185], v[56:59]
	s_add_u32 s28, s28, 0x100
	v_mfma_f32_16x16x32_bf16 v[44:47], v[144:147], v[190:193], v[44:47]
	s_addc_u32 s29, s29, 0
	v_mfma_f32_16x16x32_bf16 v[40:43], v[158:161], v[190:193], v[40:43]
	s_add_u32 s55, s55, 0x100
	v_mfma_f32_16x16x32_bf16 v[28:31], v[144:147], v[204:207], v[28:31]
	s_addc_u32 s57, s57, 0
	v_mfma_f32_16x16x32_bf16 v[24:27], v[158:161], v[204:207], v[24:27]
	s_cmp_gt_u32 s58, 13
	v_mfma_f32_16x16x32_bf16 v[12:15], v[144:147], v[212:215], v[12:15]
	v_mfma_f32_16x16x32_bf16 v[8:11], v[158:161], v[212:215], v[8:11]
	v_mfma_f32_16x16x32_bf16 v[60:63], v[154:157], v[186:189], v[60:63]
	v_mfma_f32_16x16x32_bf16 v[56:59], v[162:165], v[186:189], v[56:59]
	v_mfma_f32_16x16x32_bf16 v[44:47], v[154:157], v[200:203], v[44:47]
	v_mfma_f32_16x16x32_bf16 v[40:43], v[162:165], v[200:203], v[40:43]
	v_mfma_f32_16x16x32_bf16 v[28:31], v[154:157], v[208:211], v[28:31]
	v_mfma_f32_16x16x32_bf16 v[24:27], v[162:165], v[208:211], v[24:27]
	v_mfma_f32_16x16x32_bf16 v[12:15], v[154:157], v[216:219], v[12:15]
	v_mfma_f32_16x16x32_bf16 v[8:11], v[162:165], v[216:219], v[8:11]
	s_setprio 0
	s_setprio 1
	v_mfma_f32_16x16x32_bf16 v[52:55], v[166:169], v[182:185], v[52:55]
	v_mfma_f32_16x16x32_bf16 v[48:51], v[174:177], v[182:185], v[48:51]
	v_mfma_f32_16x16x32_bf16 v[36:39], v[166:169], v[190:193], v[36:39]
	v_mfma_f32_16x16x32_bf16 v[32:35], v[174:177], v[190:193], v[32:35]
	v_mfma_f32_16x16x32_bf16 v[20:23], v[166:169], v[204:207], v[20:23]
	v_mfma_f32_16x16x32_bf16 v[16:19], v[174:177], v[204:207], v[16:19]
	v_mfma_f32_16x16x32_bf16 v[4:7], v[166:169], v[212:215], v[4:7]
	v_mfma_f32_16x16x32_bf16 v[0:3], v[174:177], v[212:215], v[0:3]
	v_mfma_f32_16x16x32_bf16 v[52:55], v[170:173], v[186:189], v[52:55]
	v_mfma_f32_16x16x32_bf16 v[48:51], v[178:181], v[186:189], v[48:51]
	v_mfma_f32_16x16x32_bf16 v[36:39], v[170:173], v[200:203], v[36:39]
	v_mfma_f32_16x16x32_bf16 v[32:35], v[178:181], v[200:203], v[32:35]
	v_mfma_f32_16x16x32_bf16 v[20:23], v[170:173], v[208:211], v[20:23]
	v_mfma_f32_16x16x32_bf16 v[16:19], v[178:181], v[208:211], v[16:19]
	v_mfma_f32_16x16x32_bf16 v[4:7], v[170:173], v[216:219], v[4:7]
	v_mfma_f32_16x16x32_bf16 v[0:3], v[178:181], v[216:219], v[0:3]
	s_setprio 0
	s_barrier
	s_cbranch_scc0 .LBB0_1226
	s_and_b64 vcc, exec, s[14:15]
	s_cbranch_vccz .LBB0_1229
	s_barrier

.LBB0_1325:
	ds_read_b128 v[144:147], v154
	ds_read_b128 v[158:161], v154 offset:1024
	ds_read_b128 v[162:165], v154 offset:2048
	ds_read_b128 v[166:169], v154 offset:3072
	ds_read_b128 v[170:173], v155
	ds_read_b128 v[174:177], v155 offset:1024
	ds_read_b128 v[178:181], v155 offset:2048
	ds_read_b128 v[182:185], v155 offset:3072
	s_add_u32 s8, s24, 0xfffc0080
	s_addc_u32 s9, s25, -1
	s_cmp_eq_u32 s45, 12
	s_cselect_b32 s27, s15, s9
	s_cselect_b32 s26, s39, s8
	s_cselect_b32 s9, s13, s44
	s_cselect_b32 s8, s40, s41
	v_lshl_add_u64 v[148:149], s[24:25], 0, v[136:137]
	s_add_i32 m0, s4, 0xc000
	ds_read_b128 v[186:189], v156
	ds_read_b128 v[190:193], v156 offset:1024
	ds_read_b128 v[196:199], v156 offset:2048
	ds_read_b128 v[200:203], v156 offset:3072
	ds_read_b128 v[204:207], v156 offset:4096
	ds_read_b128 v[208:211], v156 offset:5120
	ds_read_b128 v[212:215], v156 offset:6144
	ds_read_b128 v[216:219], v156 offset:7168
	global_load_lds_dwordx4 v[148:149], off
	v_lshl_add_u64 v[148:149], s[24:25], 0, v[138:139]
	s_add_i32 m0, s4, 0xe000
	s_nop 0
	global_load_lds_dwordx4 v[148:149], off
	s_waitcnt vmcnt(8)
	s_waitcnt lgkmcnt(0)
	s_barrier
	s_setprio 1
	s_waitcnt lgkmcnt(0)
	v_mfma_f32_16x16x32_bf16 v[124:127], v[144:147], v[186:189], v[124:127]
	v_mfma_f32_16x16x32_bf16 v[120:123], v[162:165], v[186:189], v[120:123]
	v_mfma_f32_16x16x32_bf16 v[108:111], v[144:147], v[196:199], v[108:111]
	v_mfma_f32_16x16x32_bf16 v[104:107], v[162:165], v[196:199], v[104:107]
	v_mfma_f32_16x16x32_bf16 v[92:95], v[144:147], v[204:207], v[92:95]
	v_mfma_f32_16x16x32_bf16 v[88:91], v[162:165], v[204:207], v[88:91]
	v_mfma_f32_16x16x32_bf16 v[76:79], v[144:147], v[212:215], v[76:79]
	v_mfma_f32_16x16x32_bf16 v[72:75], v[162:165], v[212:215], v[72:75]
	v_mfma_f32_16x16x32_bf16 v[124:127], v[158:161], v[190:193], v[124:127]
	v_mfma_f32_16x16x32_bf16 v[120:123], v[166:169], v[190:193], v[120:123]
	v_mfma_f32_16x16x32_bf16 v[108:111], v[158:161], v[200:203], v[108:111]
	v_mfma_f32_16x16x32_bf16 v[104:107], v[166:169], v[200:203], v[104:107]
	v_mfma_f32_16x16x32_bf16 v[92:95], v[158:161], v[208:211], v[92:95]
	v_mfma_f32_16x16x32_bf16 v[88:91], v[166:169], v[208:211], v[88:91]
	v_mfma_f32_16x16x32_bf16 v[76:79], v[158:161], v[216:219], v[76:79]
	v_mfma_f32_16x16x32_bf16 v[72:75], v[166:169], v[216:219], v[72:75]
	s_setprio 0
	s_setprio 1
	v_mfma_f32_16x16x32_bf16 v[116:119], v[170:173], v[186:189], v[116:119]
	v_mfma_f32_16x16x32_bf16 v[112:115], v[178:181], v[186:189], v[112:115]
	v_mfma_f32_16x16x32_bf16 v[100:103], v[170:173], v[196:199], v[100:103]
	v_mfma_f32_16x16x32_bf16 v[96:99], v[178:181], v[196:199], v[96:99]
	v_mfma_f32_16x16x32_bf16 v[84:87], v[170:173], v[204:207], v[84:87]
	v_mfma_f32_16x16x32_bf16 v[80:83], v[178:181], v[204:207], v[80:83]
	v_mfma_f32_16x16x32_bf16 v[68:71], v[170:173], v[212:215], v[68:71]
	v_mfma_f32_16x16x32_bf16 v[64:67], v[178:181], v[212:215], v[64:67]
	v_mfma_f32_16x16x32_bf16 v[116:119], v[174:177], v[190:193], v[116:119]
	v_mfma_f32_16x16x32_bf16 v[112:115], v[182:185], v[190:193], v[112:115]
	v_mfma_f32_16x16x32_bf16 v[100:103], v[174:177], v[200:203], v[100:103]
	v_mfma_f32_16x16x32_bf16 v[96:99], v[182:185], v[200:203], v[96:99]
	v_mfma_f32_16x16x32_bf16 v[84:87], v[174:177], v[208:211], v[84:87]
	v_mfma_f32_16x16x32_bf16 v[80:83], v[182:185], v[208:211], v[80:83]
	v_mfma_f32_16x16x32_bf16 v[68:71], v[174:177], v[216:219], v[68:71]
	v_mfma_f32_16x16x32_bf16 v[64:67], v[182:185], v[216:219], v[64:67]
	s_setprio 0
	s_barrier
	s_add_i32 s46, s31, s3
	v_lshl_add_u64 v[148:149], s[8:9], 0, v[132:133]
	s_mov_b32 m0, s46
	ds_read_b128 v[186:189], v156 offset:16384
	ds_read_b128 v[190:193], v156 offset:17408
	ds_read_b128 v[196:199], v156 offset:18432
	ds_read_b128 v[200:203], v156 offset:19456
	ds_read_b128 v[204:207], v156 offset:20480
	ds_read_b128 v[208:211], v156 offset:21504
	ds_read_b128 v[212:215], v156 offset:22528
	ds_read_b128 v[216:219], v156 offset:23552
	global_load_lds_dwordx4 v[148:149], off
	s_add_i32 m0, s46, 0x2000
	s_add_u32 s46, s8, 0x40000
	v_lshl_add_u64 v[220:221], s[8:9], 0, v[128:129]
	s_addc_u32 s47, s9, 0
	s_add_i32 s50, s33, s3
	global_load_lds_dwordx4 v[220:221], off
	v_lshl_add_u64 v[222:223], s[46:47], 0, v[132:133]
	s_mov_b32 m0, s50
	v_lshl_add_u64 v[224:225], s[26:27], 0, v[130:131]
	global_load_lds_dwordx4 v[222:223], off
	v_lshl_add_u64 v[222:223], s[46:47], 0, v[128:129]
	s_add_i32 m0, s50, 0x2000
	s_nop 0
	global_load_lds_dwordx4 v[222:223], off
	v_lshl_add_u64 v[222:223], s[26:27], 0, v[134:135]
	s_mov_b32 m0, s4
	s_nop 0
	global_load_lds_dwordx4 v[222:223], off
	s_mov_b32 m0, s5
	s_nop 0
	global_load_lds_dwordx4 v[224:225], off
	s_waitcnt vmcnt(8)
	s_waitcnt lgkmcnt(0)
	s_barrier
	s_setprio 1
	s_waitcnt lgkmcnt(0)
	v_mfma_f32_16x16x32_bf16 v[60:63], v[144:147], v[186:189], v[60:63]
	v_mfma_f32_16x16x32_bf16 v[56:59], v[162:165], v[186:189], v[56:59]
	v_mfma_f32_16x16x32_bf16 v[44:47], v[144:147], v[196:199], v[44:47]
	v_mfma_f32_16x16x32_bf16 v[40:43], v[162:165], v[196:199], v[40:43]
	v_mfma_f32_16x16x32_bf16 v[28:31], v[144:147], v[204:207], v[28:31]
	v_mfma_f32_16x16x32_bf16 v[24:27], v[162:165], v[204:207], v[24:27]
	v_mfma_f32_16x16x32_bf16 v[12:15], v[144:147], v[212:215], v[12:15]
	v_mfma_f32_16x16x32_bf16 v[8:11], v[162:165], v[212:215], v[8:11]
	v_mfma_f32_16x16x32_bf16 v[60:63], v[158:161], v[190:193], v[60:63]
	v_mfma_f32_16x16x32_bf16 v[56:59], v[166:169], v[190:193], v[56:59]
	v_mfma_f32_16x16x32_bf16 v[44:47], v[158:161], v[200:203], v[44:47]
	v_mfma_f32_16x16x32_bf16 v[40:43], v[166:169], v[200:203], v[40:43]
	v_mfma_f32_16x16x32_bf16 v[28:31], v[158:161], v[208:211], v[28:31]
	v_mfma_f32_16x16x32_bf16 v[24:27], v[166:169], v[208:211], v[24:27]
	v_mfma_f32_16x16x32_bf16 v[12:15], v[158:161], v[216:219], v[12:15]
	v_mfma_f32_16x16x32_bf16 v[8:11], v[166:169], v[216:219], v[8:11]
	s_setprio 0
	s_setprio 1
	v_mfma_f32_16x16x32_bf16 v[52:55], v[170:173], v[186:189], v[52:55]
	v_mfma_f32_16x16x32_bf16 v[48:51], v[178:181], v[186:189], v[48:51]
	v_mfma_f32_16x16x32_bf16 v[36:39], v[170:173], v[196:199], v[36:39]
	v_mfma_f32_16x16x32_bf16 v[32:35], v[178:181], v[196:199], v[32:35]
	v_mfma_f32_16x16x32_bf16 v[20:23], v[170:173], v[204:207], v[20:23]
	v_mfma_f32_16x16x32_bf16 v[16:19], v[178:181], v[204:207], v[16:19]
	v_mfma_f32_16x16x32_bf16 v[4:7], v[170:173], v[212:215], v[4:7]
	v_mfma_f32_16x16x32_bf16 v[0:3], v[178:181], v[212:215], v[0:3]
	v_mfma_f32_16x16x32_bf16 v[52:55], v[174:177], v[190:193], v[52:55]
	v_mfma_f32_16x16x32_bf16 v[48:51], v[182:185], v[190:193], v[48:51]
	v_mfma_f32_16x16x32_bf16 v[36:39], v[174:177], v[200:203], v[36:39]
	v_mfma_f32_16x16x32_bf16 v[32:35], v[182:185], v[200:203], v[32:35]
	v_mfma_f32_16x16x32_bf16 v[20:23], v[174:177], v[208:211], v[20:23]
	v_mfma_f32_16x16x32_bf16 v[16:19], v[182:185], v[208:211], v[16:19]
	v_mfma_f32_16x16x32_bf16 v[4:7], v[174:177], v[216:219], v[4:7]
	v_mfma_f32_16x16x32_bf16 v[0:3], v[182:185], v[216:219], v[0:3]
	s_setprio 0
	s_barrier
	s_add_i32 s46, 0, 0x18000
	v_add_u32_e32 v157, s46, v151
	s_add_i32 s47, 0, 0x1c000
	ds_read_b128 v[144:147], v157
	ds_read_b128 v[158:161], v157 offset:1024
	ds_read_b128 v[162:165], v157 offset:2048
	ds_read_b128 v[166:169], v157 offset:3072
	v_add_u32_e32 v157, s47, v151
	ds_read_b128 v[170:173], v157
	ds_read_b128 v[174:177], v157 offset:1024
	ds_read_b128 v[178:181], v157 offset:2048
	ds_read_b128 v[182:185], v157 offset:3072
	s_add_u32 s26, s26, 0x40000
	s_addc_u32 s27, s27, 0
	s_mov_b32 m0, s23
	v_lshl_add_u64 v[226:227], s[26:27], 0, v[134:135]
	ds_read_b128 v[186:189], v156 offset:32768
	ds_read_b128 v[190:193], v156 offset:33792
	ds_read_b128 v[196:199], v156 offset:34816
	ds_read_b128 v[200:203], v156 offset:35840
	ds_read_b128 v[204:207], v156 offset:36864
	ds_read_b128 v[208:211], v156 offset:37888
	ds_read_b128 v[212:215], v156 offset:38912
	ds_read_b128 v[216:219], v156 offset:39936
	global_load_lds_dwordx4 v[226:227], off
	v_lshl_add_u64 v[226:227], s[26:27], 0, v[130:131]
	s_mov_b32 m0, s28
	s_nop 0
	global_load_lds_dwordx4 v[226:227], off
	s_waitcnt vmcnt(8)
	s_waitcnt lgkmcnt(0)
	s_barrier
	s_setprio 1
	s_waitcnt lgkmcnt(0)
	v_mfma_f32_16x16x32_bf16 v[124:127], v[144:147], v[186:189], v[124:127]
	v_mfma_f32_16x16x32_bf16 v[120:123], v[162:165], v[186:189], v[120:123]
	v_mfma_f32_16x16x32_bf16 v[108:111], v[144:147], v[196:199], v[108:111]
	v_mfma_f32_16x16x32_bf16 v[104:107], v[162:165], v[196:199], v[104:107]
	v_mfma_f32_16x16x32_bf16 v[92:95], v[144:147], v[204:207], v[92:95]
	v_mfma_f32_16x16x32_bf16 v[88:91], v[162:165], v[204:207], v[88:91]
	v_mfma_f32_16x16x32_bf16 v[76:79], v[144:147], v[212:215], v[76:79]
	v_mfma_f32_16x16x32_bf16 v[72:75], v[162:165], v[212:215], v[72:75]
	v_mfma_f32_16x16x32_bf16 v[124:127], v[158:161], v[190:193], v[124:127]
	v_mfma_f32_16x16x32_bf16 v[120:123], v[166:169], v[190:193], v[120:123]
	v_mfma_f32_16x16x32_bf16 v[108:111], v[158:161], v[200:203], v[108:111]
	v_mfma_f32_16x16x32_bf16 v[104:107], v[166:169], v[200:203], v[104:107]
	v_mfma_f32_16x16x32_bf16 v[92:95], v[158:161], v[208:211], v[92:95]
	v_mfma_f32_16x16x32_bf16 v[88:91], v[166:169], v[208:211], v[88:91]
	v_mfma_f32_16x16x32_bf16 v[76:79], v[158:161], v[216:219], v[76:79]
	v_mfma_f32_16x16x32_bf16 v[72:75], v[166:169], v[216:219], v[72:75]
	s_setprio 0
	s_setprio 1
	v_mfma_f32_16x16x32_bf16 v[116:119], v[170:173], v[186:189], v[116:119]
	v_mfma_f32_16x16x32_bf16 v[112:115], v[178:181], v[186:189], v[112:115]
	v_mfma_f32_16x16x32_bf16 v[100:103], v[170:173], v[196:199], v[100:103]
	v_mfma_f32_16x16x32_bf16 v[96:99], v[178:181], v[196:199], v[96:99]
	v_mfma_f32_16x16x32_bf16 v[84:87], v[170:173], v[204:207], v[84:87]
	v_mfma_f32_16x16x32_bf16 v[80:83], v[178:181], v[204:207], v[80:83]
	v_mfma_f32_16x16x32_bf16 v[68:71], v[170:173], v[212:215], v[68:71]
	v_mfma_f32_16x16x32_bf16 v[64:67], v[178:181], v[212:215], v[64:67]
	v_mfma_f32_16x16x32_bf16 v[116:119], v[174:177], v[190:193], v[116:119]
	v_mfma_f32_16x16x32_bf16 v[112:115], v[182:185], v[190:193], v[112:115]
	v_mfma_f32_16x16x32_bf16 v[100:103], v[174:177], v[200:203], v[100:103]
	v_mfma_f32_16x16x32_bf16 v[96:99], v[182:185], v[200:203], v[96:99]
	v_mfma_f32_16x16x32_bf16 v[84:87], v[174:177], v[208:211], v[84:87]
	v_mfma_f32_16x16x32_bf16 v[80:83], v[182:185], v[208:211], v[80:83]
	v_mfma_f32_16x16x32_bf16 v[68:71], v[174:177], v[216:219], v[68:71]
	v_mfma_f32_16x16x32_bf16 v[64:67], v[182:185], v[216:219], v[64:67]
	s_setprio 0
	s_barrier
	s_add_i32 s26, s46, s3
	v_lshl_add_u64 v[148:149], v[148:149], 0, s[6:7]
	s_mov_b32 m0, s26
	ds_read_b128 v[186:189], v156 offset:49152
	ds_read_b128 v[190:193], v156 offset:50176
	ds_read_b128 v[196:199], v156 offset:51200
	ds_read_b128 v[200:203], v156 offset:52224
	ds_read_b128 v[204:207], v156 offset:53248
	ds_read_b128 v[208:211], v156 offset:54272
	ds_read_b128 v[212:215], v156 offset:55296
	ds_read_b128 v[216:219], v156 offset:56320
	global_load_lds_dwordx4 v[148:149], off
	s_add_i32 m0, s26, 0x2000
	s_add_u32 s8, s8, 0x40080
	v_lshl_add_u64 v[148:149], v[220:221], 0, s[6:7]
	s_addc_u32 s9, s9, 0
	s_add_i32 s26, s47, s3
	global_load_lds_dwordx4 v[148:149], off
	v_lshl_add_u64 v[148:149], s[8:9], 0, v[132:133]
	s_mov_b32 m0, s26
	s_nop 0
	global_load_lds_dwordx4 v[148:149], off
	v_lshl_add_u64 v[148:149], s[8:9], 0, v[128:129]
	s_add_i32 m0, s26, 0x2000
	s_nop 0
	global_load_lds_dwordx4 v[148:149], off
	v_lshl_add_u64 v[148:149], v[222:223], 0, s[6:7]
	s_mov_b32 m0, s29
	s_nop 0
	global_load_lds_dwordx4 v[148:149], off
	v_lshl_add_u64 v[148:149], v[224:225], 0, s[6:7]
	s_mov_b32 m0, s30
	s_nop 0
	global_load_lds_dwordx4 v[148:149], off
	s_waitcnt vmcnt(8)
	s_waitcnt lgkmcnt(0)
	s_barrier
	s_setprio 1
	s_waitcnt lgkmcnt(0)
	v_mfma_f32_16x16x32_bf16 v[60:63], v[144:147], v[186:189], v[60:63]
	s_add_i32 s45, s45, 2
	v_mfma_f32_16x16x32_bf16 v[56:59], v[162:165], v[186:189], v[56:59]
	s_add_u32 s24, s24, 0x100
	v_mfma_f32_16x16x32_bf16 v[44:47], v[144:147], v[196:199], v[44:47]
	s_addc_u32 s25, s25, 0
	v_mfma_f32_16x16x32_bf16 v[40:43], v[162:165], v[196:199], v[40:43]
	s_add_u32 s41, s41, 0x100
	v_mfma_f32_16x16x32_bf16 v[28:31], v[144:147], v[204:207], v[28:31]
	s_addc_u32 s44, s44, 0
	v_mfma_f32_16x16x32_bf16 v[24:27], v[162:165], v[204:207], v[24:27]
	s_cmp_gt_u32 s45, 13
	v_mfma_f32_16x16x32_bf16 v[12:15], v[144:147], v[212:215], v[12:15]
	v_mfma_f32_16x16x32_bf16 v[8:11], v[162:165], v[212:215], v[8:11]
	v_mfma_f32_16x16x32_bf16 v[60:63], v[158:161], v[190:193], v[60:63]
	v_mfma_f32_16x16x32_bf16 v[56:59], v[166:169], v[190:193], v[56:59]
	v_mfma_f32_16x16x32_bf16 v[44:47], v[158:161], v[200:203], v[44:47]
	v_mfma_f32_16x16x32_bf16 v[40:43], v[166:169], v[200:203], v[40:43]
	v_mfma_f32_16x16x32_bf16 v[28:31], v[158:161], v[208:211], v[28:31]
	v_mfma_f32_16x16x32_bf16 v[24:27], v[166:169], v[208:211], v[24:27]
	v_mfma_f32_16x16x32_bf16 v[12:15], v[158:161], v[216:219], v[12:15]
	v_mfma_f32_16x16x32_bf16 v[8:11], v[166:169], v[216:219], v[8:11]
	s_setprio 0
	s_setprio 1
	v_mfma_f32_16x16x32_bf16 v[52:55], v[170:173], v[186:189], v[52:55]
	v_mfma_f32_16x16x32_bf16 v[48:51], v[178:181], v[186:189], v[48:51]
	v_mfma_f32_16x16x32_bf16 v[36:39], v[170:173], v[196:199], v[36:39]
	v_mfma_f32_16x16x32_bf16 v[32:35], v[178:181], v[196:199], v[32:35]
	v_mfma_f32_16x16x32_bf16 v[20:23], v[170:173], v[204:207], v[20:23]
	v_mfma_f32_16x16x32_bf16 v[16:19], v[178:181], v[204:207], v[16:19]
	v_mfma_f32_16x16x32_bf16 v[4:7], v[170:173], v[212:215], v[4:7]
	v_mfma_f32_16x16x32_bf16 v[0:3], v[178:181], v[212:215], v[0:3]
	v_mfma_f32_16x16x32_bf16 v[52:55], v[174:177], v[190:193], v[52:55]
	v_mfma_f32_16x16x32_bf16 v[48:51], v[182:185], v[190:193], v[48:51]
	v_mfma_f32_16x16x32_bf16 v[36:39], v[174:177], v[200:203], v[36:39]
	v_mfma_f32_16x16x32_bf16 v[32:35], v[182:185], v[200:203], v[32:35]
	v_mfma_f32_16x16x32_bf16 v[20:23], v[174:177], v[208:211], v[20:23]
	v_mfma_f32_16x16x32_bf16 v[16:19], v[182:185], v[208:211], v[16:19]
	v_mfma_f32_16x16x32_bf16 v[4:7], v[174:177], v[216:219], v[4:7]
	v_mfma_f32_16x16x32_bf16 v[0:3], v[182:185], v[216:219], v[0:3]
	s_setprio 0
	s_barrier
	s_cbranch_scc0 .LBB0_1325
	s_and_b64 vcc, exec, s[10:11]
	s_cbranch_vccz .LBB0_1328
	s_barrier

.LBB0_1399:
	ds_read_b128 v[144:147], v153
	ds_read_b128 v[156:159], v153 offset:1024
	ds_read_b128 v[160:163], v153 offset:2048
	ds_read_b128 v[164:167], v153 offset:3072
	ds_read_b128 v[168:171], v154
	ds_read_b128 v[172:175], v154 offset:1024
	ds_read_b128 v[176:179], v154 offset:2048
	ds_read_b128 v[180:183], v154 offset:3072
	s_add_u32 s36, s34, 0xfff00080
	s_addc_u32 s37, s35, -1
	s_cmp_eq_u32 s50, 60
	s_cselect_b32 s39, s25, s37
	s_cselect_b32 s38, s46, s36
	s_cselect_b32 s37, s23, s49
	s_cselect_b32 s36, s47, s48
	v_lshl_add_u64 v[148:149], s[34:35], 0, v[136:137]
	s_add_i32 m0, s4, 0xc000
	ds_read_b128 v[184:187], v155
	ds_read_b128 v[188:191], v155 offset:1024
	ds_read_b128 v[192:195], v155 offset:2048
	ds_read_b128 v[196:199], v155 offset:3072
	ds_read_b128 v[200:203], v155 offset:4096
	ds_read_b128 v[204:207], v155 offset:5120
	ds_read_b128 v[208:211], v155 offset:6144
	ds_read_b128 v[212:215], v155 offset:7168
	global_load_lds_dwordx4 v[148:149], off
	v_lshl_add_u64 v[148:149], s[34:35], 0, v[138:139]
	s_add_i32 m0, s4, 0xe000
	s_nop 0
	global_load_lds_dwordx4 v[148:149], off
	s_waitcnt vmcnt(8)
	s_waitcnt lgkmcnt(0)
	s_barrier
	s_setprio 1
	s_waitcnt lgkmcnt(0)
	v_mfma_f32_16x16x32_bf16 v[124:127], v[144:147], v[184:187], v[124:127]
	v_mfma_f32_16x16x32_bf16 v[120:123], v[160:163], v[184:187], v[120:123]
	v_mfma_f32_16x16x32_bf16 v[108:111], v[144:147], v[192:195], v[108:111]
	v_mfma_f32_16x16x32_bf16 v[104:107], v[160:163], v[192:195], v[104:107]
	v_mfma_f32_16x16x32_bf16 v[92:95], v[144:147], v[200:203], v[92:95]
	v_mfma_f32_16x16x32_bf16 v[88:91], v[160:163], v[200:203], v[88:91]
	v_mfma_f32_16x16x32_bf16 v[76:79], v[144:147], v[208:211], v[76:79]
	v_mfma_f32_16x16x32_bf16 v[72:75], v[160:163], v[208:211], v[72:75]
	v_mfma_f32_16x16x32_bf16 v[124:127], v[156:159], v[188:191], v[124:127]
	v_mfma_f32_16x16x32_bf16 v[120:123], v[164:167], v[188:191], v[120:123]
	v_mfma_f32_16x16x32_bf16 v[108:111], v[156:159], v[196:199], v[108:111]
	v_mfma_f32_16x16x32_bf16 v[104:107], v[164:167], v[196:199], v[104:107]
	v_mfma_f32_16x16x32_bf16 v[92:95], v[156:159], v[204:207], v[92:95]
	v_mfma_f32_16x16x32_bf16 v[88:91], v[164:167], v[204:207], v[88:91]
	v_mfma_f32_16x16x32_bf16 v[76:79], v[156:159], v[212:215], v[76:79]
	v_mfma_f32_16x16x32_bf16 v[72:75], v[164:167], v[212:215], v[72:75]
	s_setprio 0
	s_setprio 1
	v_mfma_f32_16x16x32_bf16 v[116:119], v[168:171], v[184:187], v[116:119]
	v_mfma_f32_16x16x32_bf16 v[112:115], v[176:179], v[184:187], v[112:115]
	v_mfma_f32_16x16x32_bf16 v[100:103], v[168:171], v[192:195], v[100:103]
	v_mfma_f32_16x16x32_bf16 v[96:99], v[176:179], v[192:195], v[96:99]
	v_mfma_f32_16x16x32_bf16 v[84:87], v[168:171], v[200:203], v[84:87]
	v_mfma_f32_16x16x32_bf16 v[80:83], v[176:179], v[200:203], v[80:83]
	v_mfma_f32_16x16x32_bf16 v[68:71], v[168:171], v[208:211], v[68:71]
	v_mfma_f32_16x16x32_bf16 v[64:67], v[176:179], v[208:211], v[64:67]
	v_mfma_f32_16x16x32_bf16 v[116:119], v[172:175], v[188:191], v[116:119]
	v_mfma_f32_16x16x32_bf16 v[112:115], v[180:183], v[188:191], v[112:115]
	v_mfma_f32_16x16x32_bf16 v[100:103], v[172:175], v[196:199], v[100:103]
	v_mfma_f32_16x16x32_bf16 v[96:99], v[180:183], v[196:199], v[96:99]
	v_mfma_f32_16x16x32_bf16 v[84:87], v[172:175], v[204:207], v[84:87]
	v_mfma_f32_16x16x32_bf16 v[80:83], v[180:183], v[204:207], v[80:83]
	v_mfma_f32_16x16x32_bf16 v[68:71], v[172:175], v[212:215], v[68:71]
	v_mfma_f32_16x16x32_bf16 v[64:67], v[180:183], v[212:215], v[64:67]
	s_setprio 0
	s_barrier
	s_add_i32 s51, s43, s3
	v_lshl_add_u64 v[148:149], s[36:37], 0, v[132:133]
	s_mov_b32 m0, s51
	ds_read_b128 v[184:187], v155 offset:16384
	ds_read_b128 v[188:191], v155 offset:17408
	ds_read_b128 v[192:195], v155 offset:18432
	ds_read_b128 v[196:199], v155 offset:19456
	ds_read_b128 v[200:203], v155 offset:20480
	ds_read_b128 v[204:207], v155 offset:21504
	ds_read_b128 v[208:211], v155 offset:22528
	ds_read_b128 v[212:215], v155 offset:23552
	global_load_lds_dwordx4 v[148:149], off
	s_add_i32 m0, s51, 0x2000
	s_add_u32 s52, s36, 0x100000
	v_lshl_add_u64 v[216:217], s[36:37], 0, v[128:129]
	s_addc_u32 s53, s37, 0
	s_add_i32 s51, s44, s3
	global_load_lds_dwordx4 v[216:217], off
	v_lshl_add_u64 v[218:219], s[52:53], 0, v[132:133]
	s_mov_b32 m0, s51
	v_lshl_add_u64 v[220:221], s[38:39], 0, v[130:131]
	global_load_lds_dwordx4 v[218:219], off
	v_lshl_add_u64 v[218:219], s[52:53], 0, v[128:129]
	s_add_i32 m0, s51, 0x2000
	s_nop 0
	global_load_lds_dwordx4 v[218:219], off
	v_lshl_add_u64 v[218:219], s[38:39], 0, v[134:135]
	s_mov_b32 m0, s4
	s_nop 0
	global_load_lds_dwordx4 v[218:219], off
	s_mov_b32 m0, s5
	s_nop 0
	global_load_lds_dwordx4 v[220:221], off
	s_waitcnt vmcnt(8)
	s_waitcnt lgkmcnt(0)
	s_barrier
	s_setprio 1
	s_waitcnt lgkmcnt(0)
	v_mfma_f32_16x16x32_bf16 v[60:63], v[144:147], v[184:187], v[60:63]
	v_mfma_f32_16x16x32_bf16 v[56:59], v[160:163], v[184:187], v[56:59]
	v_mfma_f32_16x16x32_bf16 v[44:47], v[144:147], v[192:195], v[44:47]
	v_mfma_f32_16x16x32_bf16 v[40:43], v[160:163], v[192:195], v[40:43]
	v_mfma_f32_16x16x32_bf16 v[28:31], v[144:147], v[200:203], v[28:31]
	v_mfma_f32_16x16x32_bf16 v[24:27], v[160:163], v[200:203], v[24:27]
	v_mfma_f32_16x16x32_bf16 v[12:15], v[144:147], v[208:211], v[12:15]
	v_mfma_f32_16x16x32_bf16 v[8:11], v[160:163], v[208:211], v[8:11]
	v_mfma_f32_16x16x32_bf16 v[60:63], v[156:159], v[188:191], v[60:63]
	v_mfma_f32_16x16x32_bf16 v[56:59], v[164:167], v[188:191], v[56:59]
	v_mfma_f32_16x16x32_bf16 v[44:47], v[156:159], v[196:199], v[44:47]
	v_mfma_f32_16x16x32_bf16 v[40:43], v[164:167], v[196:199], v[40:43]
	v_mfma_f32_16x16x32_bf16 v[28:31], v[156:159], v[204:207], v[28:31]
	v_mfma_f32_16x16x32_bf16 v[24:27], v[164:167], v[204:207], v[24:27]
	v_mfma_f32_16x16x32_bf16 v[12:15], v[156:159], v[212:215], v[12:15]
	v_mfma_f32_16x16x32_bf16 v[8:11], v[164:167], v[212:215], v[8:11]
	s_setprio 0
	s_setprio 1
	v_mfma_f32_16x16x32_bf16 v[52:55], v[168:171], v[184:187], v[52:55]
	v_mfma_f32_16x16x32_bf16 v[48:51], v[176:179], v[184:187], v[48:51]
	v_mfma_f32_16x16x32_bf16 v[36:39], v[168:171], v[192:195], v[36:39]
	v_mfma_f32_16x16x32_bf16 v[32:35], v[176:179], v[192:195], v[32:35]
	v_mfma_f32_16x16x32_bf16 v[20:23], v[168:171], v[200:203], v[20:23]
	v_mfma_f32_16x16x32_bf16 v[16:19], v[176:179], v[200:203], v[16:19]
	v_mfma_f32_16x16x32_bf16 v[4:7], v[168:171], v[208:211], v[4:7]
	v_mfma_f32_16x16x32_bf16 v[0:3], v[176:179], v[208:211], v[0:3]
	v_mfma_f32_16x16x32_bf16 v[52:55], v[172:175], v[188:191], v[52:55]
	v_mfma_f32_16x16x32_bf16 v[48:51], v[180:183], v[188:191], v[48:51]
	v_mfma_f32_16x16x32_bf16 v[36:39], v[172:175], v[196:199], v[36:39]
	v_mfma_f32_16x16x32_bf16 v[32:35], v[180:183], v[196:199], v[32:35]
	v_mfma_f32_16x16x32_bf16 v[20:23], v[172:175], v[204:207], v[20:23]
	v_mfma_f32_16x16x32_bf16 v[16:19], v[180:183], v[204:207], v[16:19]
	v_mfma_f32_16x16x32_bf16 v[4:7], v[172:175], v[212:215], v[4:7]
	v_mfma_f32_16x16x32_bf16 v[0:3], v[180:183], v[212:215], v[0:3]
	s_setprio 0
	s_barrier
	s_add_i32 s51, 0, 0x18000
	s_add_i32 s52, 0, 0x1c000
	v_add_u32_e32 v164, s51, v151
	v_add_u32_e32 v180, s52, v151
	ds_read_b128 v[144:147], v164
	ds_read_b128 v[156:159], v164 offset:1024
	ds_read_b128 v[160:163], v164 offset:2048
	ds_read_b128 v[164:167], v164 offset:3072
	ds_read_b128 v[168:171], v180
	ds_read_b128 v[172:175], v180 offset:1024
	ds_read_b128 v[176:179], v180 offset:2048
	ds_read_b128 v[180:183], v180 offset:3072
	s_add_u32 s38, s38, 0x100000
	s_addc_u32 s39, s39, 0
	s_mov_b32 m0, s31
	v_lshl_add_u64 v[222:223], s[38:39], 0, v[134:135]
	ds_read_b128 v[184:187], v155 offset:32768
	ds_read_b128 v[188:191], v155 offset:33792
	ds_read_b128 v[192:195], v155 offset:34816
	ds_read_b128 v[196:199], v155 offset:35840
	ds_read_b128 v[200:203], v155 offset:36864
	ds_read_b128 v[204:207], v155 offset:37888
	ds_read_b128 v[208:211], v155 offset:38912
	ds_read_b128 v[212:215], v155 offset:39936
	global_load_lds_dwordx4 v[222:223], off
	v_lshl_add_u64 v[222:223], s[38:39], 0, v[130:131]
	s_mov_b32 m0, s33
	s_nop 0
	global_load_lds_dwordx4 v[222:223], off
	s_waitcnt vmcnt(8)
	s_waitcnt lgkmcnt(0)
	s_barrier
	s_setprio 1
	s_waitcnt lgkmcnt(0)
	v_mfma_f32_16x16x32_bf16 v[124:127], v[144:147], v[184:187], v[124:127]
	v_mfma_f32_16x16x32_bf16 v[120:123], v[160:163], v[184:187], v[120:123]
	v_mfma_f32_16x16x32_bf16 v[108:111], v[144:147], v[192:195], v[108:111]
	v_mfma_f32_16x16x32_bf16 v[104:107], v[160:163], v[192:195], v[104:107]
	v_mfma_f32_16x16x32_bf16 v[92:95], v[144:147], v[200:203], v[92:95]
	v_mfma_f32_16x16x32_bf16 v[88:91], v[160:163], v[200:203], v[88:91]
	v_mfma_f32_16x16x32_bf16 v[76:79], v[144:147], v[208:211], v[76:79]
	v_mfma_f32_16x16x32_bf16 v[72:75], v[160:163], v[208:211], v[72:75]
	v_mfma_f32_16x16x32_bf16 v[124:127], v[156:159], v[188:191], v[124:127]
	v_mfma_f32_16x16x32_bf16 v[120:123], v[164:167], v[188:191], v[120:123]
	v_mfma_f32_16x16x32_bf16 v[108:111], v[156:159], v[196:199], v[108:111]
	v_mfma_f32_16x16x32_bf16 v[104:107], v[164:167], v[196:199], v[104:107]
	v_mfma_f32_16x16x32_bf16 v[92:95], v[156:159], v[204:207], v[92:95]
	v_mfma_f32_16x16x32_bf16 v[88:91], v[164:167], v[204:207], v[88:91]
	v_mfma_f32_16x16x32_bf16 v[76:79], v[156:159], v[212:215], v[76:79]
	v_mfma_f32_16x16x32_bf16 v[72:75], v[164:167], v[212:215], v[72:75]
	s_setprio 0
	s_setprio 1
	v_mfma_f32_16x16x32_bf16 v[116:119], v[168:171], v[184:187], v[116:119]
	v_mfma_f32_16x16x32_bf16 v[112:115], v[176:179], v[184:187], v[112:115]
	v_mfma_f32_16x16x32_bf16 v[100:103], v[168:171], v[192:195], v[100:103]
	v_mfma_f32_16x16x32_bf16 v[96:99], v[176:179], v[192:195], v[96:99]
	v_mfma_f32_16x16x32_bf16 v[84:87], v[168:171], v[200:203], v[84:87]
	v_mfma_f32_16x16x32_bf16 v[80:83], v[176:179], v[200:203], v[80:83]
	v_mfma_f32_16x16x32_bf16 v[68:71], v[168:171], v[208:211], v[68:71]
	v_mfma_f32_16x16x32_bf16 v[64:67], v[176:179], v[208:211], v[64:67]
	v_mfma_f32_16x16x32_bf16 v[116:119], v[172:175], v[188:191], v[116:119]
	v_mfma_f32_16x16x32_bf16 v[112:115], v[180:183], v[188:191], v[112:115]
	v_mfma_f32_16x16x32_bf16 v[100:103], v[172:175], v[196:199], v[100:103]
	v_mfma_f32_16x16x32_bf16 v[96:99], v[180:183], v[196:199], v[96:99]
	v_mfma_f32_16x16x32_bf16 v[84:87], v[172:175], v[204:207], v[84:87]
	v_mfma_f32_16x16x32_bf16 v[80:83], v[180:183], v[204:207], v[80:83]
	v_mfma_f32_16x16x32_bf16 v[68:71], v[172:175], v[212:215], v[68:71]
	v_mfma_f32_16x16x32_bf16 v[64:67], v[180:183], v[212:215], v[64:67]
	s_setprio 0
	s_barrier
	s_add_i32 s38, s51, s3
	v_lshl_add_u64 v[148:149], v[148:149], 0, s[8:9]
	s_mov_b32 m0, s38
	ds_read_b128 v[184:187], v155 offset:49152
	ds_read_b128 v[188:191], v155 offset:50176
	ds_read_b128 v[192:195], v155 offset:51200
	ds_read_b128 v[196:199], v155 offset:52224
	ds_read_b128 v[200:203], v155 offset:53248
	ds_read_b128 v[204:207], v155 offset:54272
	ds_read_b128 v[208:211], v155 offset:55296
	ds_read_b128 v[212:215], v155 offset:56320
	global_load_lds_dwordx4 v[148:149], off
	s_add_i32 m0, s38, 0x2000
	s_add_u32 s36, s36, 0x100080
	v_lshl_add_u64 v[148:149], v[216:217], 0, s[8:9]
	s_addc_u32 s37, s37, 0
	s_add_i32 s38, s52, s3
	global_load_lds_dwordx4 v[148:149], off
	v_lshl_add_u64 v[148:149], s[36:37], 0, v[132:133]
	s_mov_b32 m0, s38
	s_nop 0
	global_load_lds_dwordx4 v[148:149], off
	v_lshl_add_u64 v[148:149], s[36:37], 0, v[128:129]
	s_add_i32 m0, s38, 0x2000
	s_nop 0
	global_load_lds_dwordx4 v[148:149], off
	v_lshl_add_u64 v[148:149], v[218:219], 0, s[8:9]
	s_mov_b32 m0, s41
	s_nop 0
	global_load_lds_dwordx4 v[148:149], off
	v_lshl_add_u64 v[148:149], v[220:221], 0, s[8:9]
	s_mov_b32 m0, s42
	s_nop 0
	global_load_lds_dwordx4 v[148:149], off
	s_waitcnt vmcnt(8)
	s_waitcnt lgkmcnt(0)
	s_barrier
	s_setprio 1
	s_waitcnt lgkmcnt(0)
	v_mfma_f32_16x16x32_bf16 v[60:63], v[144:147], v[184:187], v[60:63]
	s_add_i32 s50, s50, 2
	v_mfma_f32_16x16x32_bf16 v[56:59], v[160:163], v[184:187], v[56:59]
	s_add_u32 s34, s34, 0x100
	v_mfma_f32_16x16x32_bf16 v[44:47], v[144:147], v[192:195], v[44:47]
	s_addc_u32 s35, s35, 0
	v_mfma_f32_16x16x32_bf16 v[40:43], v[160:163], v[192:195], v[40:43]
	s_add_u32 s48, s48, 0x100
	v_mfma_f32_16x16x32_bf16 v[28:31], v[144:147], v[200:203], v[28:31]
	s_addc_u32 s49, s49, 0
	v_mfma_f32_16x16x32_bf16 v[24:27], v[160:163], v[200:203], v[24:27]
	s_cmp_gt_u32 s50, 61
	v_mfma_f32_16x16x32_bf16 v[12:15], v[144:147], v[208:211], v[12:15]
	v_mfma_f32_16x16x32_bf16 v[8:11], v[160:163], v[208:211], v[8:11]
	v_mfma_f32_16x16x32_bf16 v[60:63], v[156:159], v[188:191], v[60:63]
	v_mfma_f32_16x16x32_bf16 v[56:59], v[164:167], v[188:191], v[56:59]
	v_mfma_f32_16x16x32_bf16 v[44:47], v[156:159], v[196:199], v[44:47]
	v_mfma_f32_16x16x32_bf16 v[40:43], v[164:167], v[196:199], v[40:43]
	v_mfma_f32_16x16x32_bf16 v[28:31], v[156:159], v[204:207], v[28:31]
	v_mfma_f32_16x16x32_bf16 v[24:27], v[164:167], v[204:207], v[24:27]
	v_mfma_f32_16x16x32_bf16 v[12:15], v[156:159], v[212:215], v[12:15]
	v_mfma_f32_16x16x32_bf16 v[8:11], v[164:167], v[212:215], v[8:11]
	s_setprio 0
	s_setprio 1
	v_mfma_f32_16x16x32_bf16 v[52:55], v[168:171], v[184:187], v[52:55]
	v_mfma_f32_16x16x32_bf16 v[48:51], v[176:179], v[184:187], v[48:51]
	v_mfma_f32_16x16x32_bf16 v[36:39], v[168:171], v[192:195], v[36:39]
	v_mfma_f32_16x16x32_bf16 v[32:35], v[176:179], v[192:195], v[32:35]
	v_mfma_f32_16x16x32_bf16 v[20:23], v[168:171], v[200:203], v[20:23]
	v_mfma_f32_16x16x32_bf16 v[16:19], v[176:179], v[200:203], v[16:19]
	v_mfma_f32_16x16x32_bf16 v[4:7], v[168:171], v[208:211], v[4:7]
	v_mfma_f32_16x16x32_bf16 v[0:3], v[176:179], v[208:211], v[0:3]
	v_mfma_f32_16x16x32_bf16 v[52:55], v[172:175], v[188:191], v[52:55]
	v_mfma_f32_16x16x32_bf16 v[48:51], v[180:183], v[188:191], v[48:51]
	v_mfma_f32_16x16x32_bf16 v[36:39], v[172:175], v[196:199], v[36:39]
	v_mfma_f32_16x16x32_bf16 v[32:35], v[180:183], v[196:199], v[32:35]
	v_mfma_f32_16x16x32_bf16 v[20:23], v[172:175], v[204:207], v[20:23]
	v_mfma_f32_16x16x32_bf16 v[16:19], v[180:183], v[204:207], v[16:19]
	v_mfma_f32_16x16x32_bf16 v[4:7], v[172:175], v[212:215], v[4:7]
	v_mfma_f32_16x16x32_bf16 v[0:3], v[180:183], v[212:215], v[0:3]
	s_setprio 0
	s_barrier
	s_cbranch_scc0 .LBB0_1399
	s_and_b64 vcc, exec, s[10:11]
	s_cbranch_vccz .LBB0_1402
	s_barrier
